# p3a S4 blocked: X22 by row substitution, off-diagonal block via sixteen v_mfma_f32_32x32x2_f32 (f32 operands), X11 and X21 in one shared substitution pass; halves the VALU work of the triangular inver
# speedup vs baseline: 1.0029x; 1.0029x over previous
.LBB0_653:
	v_readlane_b32 s1, v249, 49
	v_readlane_b32 s0, v248, 20
	v_readlane_b32 s4, v248, 2
	v_readlane_b32 s5, v248, 17
	s_lshl_b32 s0, s0, 3
	s_add_i32 s0, s0, s1
	s_add_i32 s72, s72, s0
	s_lshr_b32 s1, s72, 4
	s_mov_b32 s3, 0x24300000
	s_cmp_eq_u32 s1, 2
	s_cselect_b32 s2, s3, 0x26000000
	s_cmp_lg_u32 s1, 1
	s_cselect_b32 s1, s2, 0x1d000000
	s_cmp_gt_u32 s72, 15
	s_cselect_b32 s1, s1, 0x1ed00000
	s_add_u32 s1, s70, s1
	s_addc_u32 s2, s71, 0
	s_lshl_b32 s0, s0, 6
	s_and_b32 s0, s0, 0x3c0
	s_add_i32 s0, s0, s85
	s_mul_hi_i32 s3, s0, 0x7400
	s_mulk_i32 s0, 0x7400
	s_add_u32 s6, s1, s0
	s_addc_u32 s7, s2, s3
	v_and_b32_e32 v20, 15, v1
	v_lshl_add_u32 v138, v20, 2, s4
	v_or_b32_e32 v139, 32, v1
	v_cmp_lt_u32_e64 s[2:3], 31, v1
	v_and_b32_e32 v154, 31, v1
	v_add_u32_e32 v154, 1, v154
	v_lshrrev_b32_e32 v155, 2, v154
	v_and_b32_e32 v154, 3, v154
	v_lshlrev_b32_e32 v20, 3, v155
	v_sub_u32_e32 v20, 0x104, v20
	v_mul_u32_u24_e32 v20, v155, v20
	v_lshlrev_b32_e32 v21, 2, v155
	v_sub_u32_e32 v21, 64, v21
	v_mul_u32_u24_e32 v21, v154, v21
	v_add_u32_e32 v20, v20, v21
	v_lshrrev_b32_e32 v21, 5, v1
	v_add_u32_e32 v20, v20, v21
	v_subrev_u32_e32 v20, 32, v20
	v_lshl_add_u32 v152, v20, 2, s4
	v_subrev_u32_e32 v153, 36, v1
	v_cndmask_b32_e64 v153, v1, v153, s[2:3]
	ds_read_b32 v226, v152 offset:0
	ds_read_b32 v227, v152 offset:8
	ds_read_b32 v228, v152 offset:16
	ds_read_b32 v229, v152 offset:24
	ds_read_b32 v230, v152 offset:32
	ds_read_b32 v231, v152 offset:40
	ds_read_b32 v232, v152 offset:48
	ds_read_b32 v233, v152 offset:56
	ds_read_b32 v234, v152 offset:64
	ds_read_b32 v235, v152 offset:72
	ds_read_b32 v236, v152 offset:80
	ds_read_b32 v237, v152 offset:88
	ds_read_b32 v238, v152 offset:96
	ds_read_b32 v239, v152 offset:104
	ds_read_b32 v240, v152 offset:112
	ds_read_b32 v241, v152 offset:120
	ds_read_b32 v148, v138 offset:8432
	v_cmp_eq_u32_e32 vcc, 63, v139
	s_nop 1
	v_cndmask_b32_e64 v134, 0, 1.0, vcc
	ds_read_b32 v144, v138 offset:8416
	s_waitcnt lgkmcnt(2)
	v_cmp_eq_u32_e32 vcc, 62, v139
	s_nop 1
	v_cndmask_b32_e64 v130, 0, 1.0, vcc
	v_mov_b32_e32 v129, v134
	ds_read_b32 v140, v138 offset:8400
	s_waitcnt lgkmcnt(2)
	v_cmp_eq_u32_e32 vcc, 61, v139
	v_mul_f32_dpp v133, -v148, v129 row_newbcast:3 row_mask:0xf bank_mask:0xf
	s_nop 0
	v_cndmask_b32_e64 v134, 0, 1.0, vcc
	v_add_f32_e32 v128, v130, v133
	ds_read_b32 v148, v138 offset:8384
	s_waitcnt lgkmcnt(2)
	v_cmp_eq_u32_e32 vcc, 60, v139
	v_mul_f32_dpp v137, -v144, v129 row_newbcast:3 row_mask:0xf bank_mask:0xf
	v_mul_f32_dpp v136, -v144, v128 row_newbcast:2 row_mask:0xf bank_mask:0xf
	v_cndmask_b32_e64 v130, 0, 1.0, vcc
	v_add_f32_e32 v21, v136, v137
	v_add_f32_e32 v127, v134, v21
	ds_read_b32 v144, v138 offset:8352
	s_waitcnt lgkmcnt(2)
	v_cmp_eq_u32_e32 vcc, 59, v139
	v_mul_f32_dpp v132, -v140, v128 row_newbcast:2 row_mask:0xf bank_mask:0xf
	v_mul_f32_dpp v133, -v140, v129 row_newbcast:3 row_mask:0xf bank_mask:0xf
	v_mul_f32_dpp v131, -v140, v127 row_newbcast:1 row_mask:0xf bank_mask:0xf
	v_cndmask_b32_e64 v134, 0, 1.0, vcc
	v_add_f32_e32 v20, v130, v131
	v_add_f32_e32 v21, v132, v133
	v_add_f32_e32 v126, v20, v21
	ds_read_b32 v140, v138 offset:8320
	s_waitcnt lgkmcnt(2)
	v_cmp_eq_u32_e32 vcc, 58, v139
	v_mul_f32_dpp v135, -v148, v127 row_newbcast:1 row_mask:0xf bank_mask:0xf
	v_mul_f32_dpp v136, -v148, v128 row_newbcast:2 row_mask:0xf bank_mask:0xf
	v_mul_f32_dpp v137, -v148, v129 row_newbcast:3 row_mask:0xf bank_mask:0xf
	v_fmac_f32_dpp v134, -v148, v126 row_newbcast:0 row_mask:0xf bank_mask:0xf
	v_cndmask_b32_e64 v130, 0, 1.0, vcc
	v_add_f32_e32 v20, v134, v135
	v_add_f32_e32 v21, v136, v137
	v_add_f32_e32 v125, v20, v21
	ds_read_b32 v148, v138 offset:8288
	s_waitcnt lgkmcnt(2)
	v_cmp_eq_u32_e32 vcc, 57, v139
	v_fmac_f32_dpp v130, -v144, v126 row_newbcast:4 row_mask:0xf bank_mask:0xf
	v_mul_f32_dpp v131, -v144, v127 row_newbcast:5 row_mask:0xf bank_mask:0xf
	v_mul_f32_dpp v132, -v144, v128 row_newbcast:6 row_mask:0xf bank_mask:0xf
	v_mul_f32_dpp v133, -v144, v125 row_newbcast:3 row_mask:0xf bank_mask:0xf
	s_nop 1
	v_fmac_f32_dpp v133, -v144, v129 row_newbcast:7 row_mask:0xf bank_mask:0xf
	v_cndmask_b32_e64 v134, 0, 1.0, vcc
	v_add_f32_e32 v20, v130, v131
	v_add_f32_e32 v21, v132, v133
	v_add_f32_e32 v124, v20, v21
	ds_read_b32 v144, v138 offset:8256
	s_waitcnt lgkmcnt(2)
	v_cmp_eq_u32_e32 vcc, 56, v139
	v_mul_f32_dpp v137, -v140, v125 row_newbcast:3 row_mask:0xf bank_mask:0xf
	v_fmac_f32_dpp v134, -v140, v126 row_newbcast:4 row_mask:0xf bank_mask:0xf
	v_mul_f32_dpp v135, -v140, v127 row_newbcast:5 row_mask:0xf bank_mask:0xf
	v_mul_f32_dpp v136, -v140, v124 row_newbcast:2 row_mask:0xf bank_mask:0xf
	v_fmac_f32_dpp v137, -v140, v129 row_newbcast:7 row_mask:0xf bank_mask:0xf
	s_nop 0
	v_fmac_f32_dpp v136, -v140, v128 row_newbcast:6 row_mask:0xf bank_mask:0xf
	v_cndmask_b32_e64 v130, 0, 1.0, vcc
	v_add_f32_e32 v20, v134, v135
	v_add_f32_e32 v21, v136, v137
	v_add_f32_e32 v123, v20, v21
	ds_read_b32 v140, v138 offset:8208
	s_waitcnt lgkmcnt(2)
	v_cmp_eq_u32_e32 vcc, 55, v139
	v_mul_f32_dpp v132, -v148, v124 row_newbcast:2 row_mask:0xf bank_mask:0xf
	v_mul_f32_dpp v133, -v148, v125 row_newbcast:3 row_mask:0xf bank_mask:0xf
	v_fmac_f32_dpp v130, -v148, v126 row_newbcast:4 row_mask:0xf bank_mask:0xf
	v_mul_f32_dpp v131, -v148, v123 row_newbcast:1 row_mask:0xf bank_mask:0xf
	v_fmac_f32_dpp v132, -v148, v128 row_newbcast:6 row_mask:0xf bank_mask:0xf
	v_fmac_f32_dpp v133, -v148, v129 row_newbcast:7 row_mask:0xf bank_mask:0xf
	v_fmac_f32_dpp v131, -v148, v127 row_newbcast:5 row_mask:0xf bank_mask:0xf
	v_cndmask_b32_e64 v134, 0, 1.0, vcc
	v_add_f32_e32 v20, v130, v131
	v_add_f32_e32 v21, v132, v133
	v_add_f32_e32 v122, v20, v21
	ds_read_b32 v148, v138 offset:8160
	s_waitcnt lgkmcnt(2)
	v_cmp_eq_u32_e32 vcc, 54, v139
	v_mul_f32_dpp v135, -v144, v123 row_newbcast:1 row_mask:0xf bank_mask:0xf
	v_mul_f32_dpp v136, -v144, v124 row_newbcast:2 row_mask:0xf bank_mask:0xf
	v_mul_f32_dpp v137, -v144, v125 row_newbcast:3 row_mask:0xf bank_mask:0xf
	v_fmac_f32_dpp v134, -v144, v122 row_newbcast:0 row_mask:0xf bank_mask:0xf
	v_fmac_f32_dpp v135, -v144, v127 row_newbcast:5 row_mask:0xf bank_mask:0xf
	v_fmac_f32_dpp v136, -v144, v128 row_newbcast:6 row_mask:0xf bank_mask:0xf
	v_fmac_f32_dpp v137, -v144, v129 row_newbcast:7 row_mask:0xf bank_mask:0xf
	v_fmac_f32_dpp v134, -v144, v126 row_newbcast:4 row_mask:0xf bank_mask:0xf
	v_cndmask_b32_e64 v130, 0, 1.0, vcc
	v_add_f32_e32 v20, v134, v135
	v_add_f32_e32 v21, v136, v137
	v_add_f32_e32 v121, v20, v21
	ds_read_b32 v144, v138 offset:8112
	s_waitcnt lgkmcnt(2)
	v_cmp_eq_u32_e32 vcc, 53, v139
	v_fmac_f32_dpp v130, -v140, v122 row_newbcast:4 row_mask:0xf bank_mask:0xf
	v_mul_f32_dpp v131, -v140, v123 row_newbcast:5 row_mask:0xf bank_mask:0xf
	v_mul_f32_dpp v132, -v140, v124 row_newbcast:6 row_mask:0xf bank_mask:0xf
	v_mul_f32_dpp v133, -v140, v121 row_newbcast:3 row_mask:0xf bank_mask:0xf
	v_fmac_f32_dpp v130, -v140, v126 row_newbcast:8 row_mask:0xf bank_mask:0xf
	v_fmac_f32_dpp v131, -v140, v127 row_newbcast:9 row_mask:0xf bank_mask:0xf
	v_fmac_f32_dpp v132, -v140, v128 row_newbcast:10 row_mask:0xf bank_mask:0xf
	v_fmac_f32_dpp v133, -v140, v125 row_newbcast:7 row_mask:0xf bank_mask:0xf
	s_nop 1
	v_fmac_f32_dpp v133, -v140, v129 row_newbcast:11 row_mask:0xf bank_mask:0xf
	v_cndmask_b32_e64 v134, 0, 1.0, vcc
	v_add_f32_e32 v20, v130, v131
	v_add_f32_e32 v21, v132, v133
	v_add_f32_e32 v120, v20, v21
	ds_read_b32 v140, v138 offset:8064
	s_waitcnt lgkmcnt(2)
	v_cmp_eq_u32_e32 vcc, 52, v139
	v_mul_f32_dpp v137, -v148, v121 row_newbcast:3 row_mask:0xf bank_mask:0xf
	v_fmac_f32_dpp v134, -v148, v122 row_newbcast:4 row_mask:0xf bank_mask:0xf
	v_mul_f32_dpp v135, -v148, v123 row_newbcast:5 row_mask:0xf bank_mask:0xf
	v_mul_f32_dpp v136, -v148, v120 row_newbcast:2 row_mask:0xf bank_mask:0xf
	v_fmac_f32_dpp v137, -v148, v125 row_newbcast:7 row_mask:0xf bank_mask:0xf
	v_fmac_f32_dpp v134, -v148, v126 row_newbcast:8 row_mask:0xf bank_mask:0xf
	v_fmac_f32_dpp v135, -v148, v127 row_newbcast:9 row_mask:0xf bank_mask:0xf
	v_fmac_f32_dpp v136, -v148, v124 row_newbcast:6 row_mask:0xf bank_mask:0xf
	v_fmac_f32_dpp v137, -v148, v129 row_newbcast:11 row_mask:0xf bank_mask:0xf
	s_nop 0
	v_fmac_f32_dpp v136, -v148, v128 row_newbcast:10 row_mask:0xf bank_mask:0xf
	v_cndmask_b32_e64 v130, 0, 1.0, vcc
	v_add_f32_e32 v20, v134, v135
	v_add_f32_e32 v21, v136, v137
	v_add_f32_e32 v119, v20, v21
	ds_read_b32 v148, v138 offset:8000
	s_waitcnt lgkmcnt(2)
	v_cmp_eq_u32_e32 vcc, 51, v139
	v_mul_f32_dpp v132, -v144, v120 row_newbcast:2 row_mask:0xf bank_mask:0xf
	v_mul_f32_dpp v133, -v144, v121 row_newbcast:3 row_mask:0xf bank_mask:0xf
	v_fmac_f32_dpp v130, -v144, v122 row_newbcast:4 row_mask:0xf bank_mask:0xf
	v_mul_f32_dpp v131, -v144, v119 row_newbcast:1 row_mask:0xf bank_mask:0xf
	v_fmac_f32_dpp v132, -v144, v124 row_newbcast:6 row_mask:0xf bank_mask:0xf
	v_fmac_f32_dpp v133, -v144, v125 row_newbcast:7 row_mask:0xf bank_mask:0xf
	v_fmac_f32_dpp v130, -v144, v126 row_newbcast:8 row_mask:0xf bank_mask:0xf
	v_fmac_f32_dpp v131, -v144, v123 row_newbcast:5 row_mask:0xf bank_mask:0xf
	v_fmac_f32_dpp v132, -v144, v128 row_newbcast:10 row_mask:0xf bank_mask:0xf
	v_fmac_f32_dpp v133, -v144, v129 row_newbcast:11 row_mask:0xf bank_mask:0xf
	v_fmac_f32_dpp v131, -v144, v127 row_newbcast:9 row_mask:0xf bank_mask:0xf
	v_cndmask_b32_e64 v134, 0, 1.0, vcc
	v_add_f32_e32 v20, v130, v131
	v_add_f32_e32 v21, v132, v133
	v_add_f32_e32 v118, v20, v21
	ds_read_b32 v144, v138 offset:7936
	s_waitcnt lgkmcnt(2)
	v_cmp_eq_u32_e32 vcc, 50, v139
	v_mul_f32_dpp v135, -v140, v119 row_newbcast:1 row_mask:0xf bank_mask:0xf
	v_mul_f32_dpp v136, -v140, v120 row_newbcast:2 row_mask:0xf bank_mask:0xf
	v_mul_f32_dpp v137, -v140, v121 row_newbcast:3 row_mask:0xf bank_mask:0xf
	v_fmac_f32_dpp v134, -v140, v118 row_newbcast:0 row_mask:0xf bank_mask:0xf
	v_fmac_f32_dpp v135, -v140, v123 row_newbcast:5 row_mask:0xf bank_mask:0xf
	v_fmac_f32_dpp v136, -v140, v124 row_newbcast:6 row_mask:0xf bank_mask:0xf
	v_fmac_f32_dpp v137, -v140, v125 row_newbcast:7 row_mask:0xf bank_mask:0xf
	v_fmac_f32_dpp v134, -v140, v122 row_newbcast:4 row_mask:0xf bank_mask:0xf
	v_fmac_f32_dpp v135, -v140, v127 row_newbcast:9 row_mask:0xf bank_mask:0xf
	v_fmac_f32_dpp v136, -v140, v128 row_newbcast:10 row_mask:0xf bank_mask:0xf
	v_fmac_f32_dpp v137, -v140, v129 row_newbcast:11 row_mask:0xf bank_mask:0xf
	v_fmac_f32_dpp v134, -v140, v126 row_newbcast:8 row_mask:0xf bank_mask:0xf
	v_cndmask_b32_e64 v130, 0, 1.0, vcc
	v_add_f32_e32 v20, v134, v135
	v_add_f32_e32 v21, v136, v137
	v_add_f32_e32 v117, v20, v21
	ds_read_b32 v140, v138 offset:7872
	s_waitcnt lgkmcnt(2)
	v_cmp_eq_u32_e32 vcc, 49, v139
	v_fmac_f32_dpp v130, -v148, v118 row_newbcast:4 row_mask:0xf bank_mask:0xf
	v_mul_f32_dpp v131, -v148, v119 row_newbcast:5 row_mask:0xf bank_mask:0xf
	v_mul_f32_dpp v132, -v148, v120 row_newbcast:6 row_mask:0xf bank_mask:0xf
	v_mul_f32_dpp v133, -v148, v117 row_newbcast:3 row_mask:0xf bank_mask:0xf
	v_fmac_f32_dpp v130, -v148, v122 row_newbcast:8 row_mask:0xf bank_mask:0xf
	v_fmac_f32_dpp v131, -v148, v123 row_newbcast:9 row_mask:0xf bank_mask:0xf
	v_fmac_f32_dpp v132, -v148, v124 row_newbcast:10 row_mask:0xf bank_mask:0xf
	v_fmac_f32_dpp v133, -v148, v121 row_newbcast:7 row_mask:0xf bank_mask:0xf
	v_fmac_f32_dpp v130, -v148, v126 row_newbcast:12 row_mask:0xf bank_mask:0xf
	v_fmac_f32_dpp v131, -v148, v127 row_newbcast:13 row_mask:0xf bank_mask:0xf
	v_fmac_f32_dpp v132, -v148, v128 row_newbcast:14 row_mask:0xf bank_mask:0xf
	v_fmac_f32_dpp v133, -v148, v125 row_newbcast:11 row_mask:0xf bank_mask:0xf
	s_nop 1
	v_fmac_f32_dpp v133, -v148, v129 row_newbcast:15 row_mask:0xf bank_mask:0xf
	v_cndmask_b32_e64 v134, 0, 1.0, vcc
	v_add_f32_e32 v20, v130, v131
	v_add_f32_e32 v21, v132, v133
	v_add_f32_e32 v116, v20, v21
	ds_read_b32 v148, v138 offset:7808
	s_waitcnt lgkmcnt(2)
	v_cmp_eq_u32_e32 vcc, 48, v139
	v_mul_f32_dpp v137, -v144, v117 row_newbcast:3 row_mask:0xf bank_mask:0xf
	v_fmac_f32_dpp v134, -v144, v118 row_newbcast:4 row_mask:0xf bank_mask:0xf
	v_mul_f32_dpp v135, -v144, v119 row_newbcast:5 row_mask:0xf bank_mask:0xf
	v_mul_f32_dpp v136, -v144, v116 row_newbcast:2 row_mask:0xf bank_mask:0xf
	v_fmac_f32_dpp v137, -v144, v121 row_newbcast:7 row_mask:0xf bank_mask:0xf
	v_fmac_f32_dpp v134, -v144, v122 row_newbcast:8 row_mask:0xf bank_mask:0xf
	v_fmac_f32_dpp v135, -v144, v123 row_newbcast:9 row_mask:0xf bank_mask:0xf
	v_fmac_f32_dpp v136, -v144, v120 row_newbcast:6 row_mask:0xf bank_mask:0xf
	v_fmac_f32_dpp v137, -v144, v125 row_newbcast:11 row_mask:0xf bank_mask:0xf
	v_fmac_f32_dpp v134, -v144, v126 row_newbcast:12 row_mask:0xf bank_mask:0xf
	v_fmac_f32_dpp v135, -v144, v127 row_newbcast:13 row_mask:0xf bank_mask:0xf
	v_fmac_f32_dpp v136, -v144, v124 row_newbcast:10 row_mask:0xf bank_mask:0xf
	v_fmac_f32_dpp v137, -v144, v129 row_newbcast:15 row_mask:0xf bank_mask:0xf
	s_nop 0
	v_fmac_f32_dpp v136, -v144, v128 row_newbcast:14 row_mask:0xf bank_mask:0xf
	v_cndmask_b32_e64 v130, 0, 1.0, vcc
	v_add_f32_e32 v20, v134, v135
	v_add_f32_e32 v21, v136, v137
	v_add_f32_e32 v115, v20, v21
	ds_read_b32 v144, v138 offset:7728
	ds_read_b32 v145, v138 offset:7792
	s_waitcnt lgkmcnt(3)
	v_cmp_eq_u32_e32 vcc, 47, v139
	v_mul_f32_dpp v132, -v140, v116 row_newbcast:2 row_mask:0xf bank_mask:0xf
	v_mul_f32_dpp v133, -v140, v117 row_newbcast:3 row_mask:0xf bank_mask:0xf
	v_fmac_f32_dpp v130, -v140, v118 row_newbcast:4 row_mask:0xf bank_mask:0xf
	v_mul_f32_dpp v131, -v140, v115 row_newbcast:1 row_mask:0xf bank_mask:0xf
	v_fmac_f32_dpp v132, -v140, v120 row_newbcast:6 row_mask:0xf bank_mask:0xf
	v_fmac_f32_dpp v133, -v140, v121 row_newbcast:7 row_mask:0xf bank_mask:0xf
	v_fmac_f32_dpp v130, -v140, v122 row_newbcast:8 row_mask:0xf bank_mask:0xf
	v_fmac_f32_dpp v131, -v140, v119 row_newbcast:5 row_mask:0xf bank_mask:0xf
	v_fmac_f32_dpp v132, -v140, v124 row_newbcast:10 row_mask:0xf bank_mask:0xf
	v_fmac_f32_dpp v133, -v140, v125 row_newbcast:11 row_mask:0xf bank_mask:0xf
	v_fmac_f32_dpp v130, -v140, v126 row_newbcast:12 row_mask:0xf bank_mask:0xf
	v_fmac_f32_dpp v131, -v140, v123 row_newbcast:9 row_mask:0xf bank_mask:0xf
	v_fmac_f32_dpp v132, -v140, v128 row_newbcast:14 row_mask:0xf bank_mask:0xf
	v_fmac_f32_dpp v133, -v140, v129 row_newbcast:15 row_mask:0xf bank_mask:0xf
	v_fmac_f32_dpp v131, -v140, v127 row_newbcast:13 row_mask:0xf bank_mask:0xf
	v_cndmask_b32_e64 v134, 0, 1.0, vcc
	v_add_f32_e32 v20, v130, v131
	v_add_f32_e32 v21, v132, v133
	v_add_f32_e32 v114, v20, v21
	ds_read_b32 v140, v138 offset:7648
	ds_read_b32 v141, v138 offset:7712
	s_waitcnt lgkmcnt(4)
	v_cmp_eq_u32_e32 vcc, 46, v139
	v_mul_f32_dpp v135, -v148, v115 row_newbcast:1 row_mask:0xf bank_mask:0xf
	v_mul_f32_dpp v136, -v148, v116 row_newbcast:2 row_mask:0xf bank_mask:0xf
	v_mul_f32_dpp v137, -v148, v117 row_newbcast:3 row_mask:0xf bank_mask:0xf
	v_fmac_f32_dpp v134, -v148, v114 row_newbcast:0 row_mask:0xf bank_mask:0xf
	v_fmac_f32_dpp v135, -v148, v119 row_newbcast:5 row_mask:0xf bank_mask:0xf
	v_fmac_f32_dpp v136, -v148, v120 row_newbcast:6 row_mask:0xf bank_mask:0xf
	v_fmac_f32_dpp v137, -v148, v121 row_newbcast:7 row_mask:0xf bank_mask:0xf
	v_fmac_f32_dpp v134, -v148, v118 row_newbcast:4 row_mask:0xf bank_mask:0xf
	v_fmac_f32_dpp v135, -v148, v123 row_newbcast:9 row_mask:0xf bank_mask:0xf
	v_fmac_f32_dpp v136, -v148, v124 row_newbcast:10 row_mask:0xf bank_mask:0xf
	v_fmac_f32_dpp v137, -v148, v125 row_newbcast:11 row_mask:0xf bank_mask:0xf
	v_fmac_f32_dpp v134, -v148, v122 row_newbcast:8 row_mask:0xf bank_mask:0xf
	v_fmac_f32_dpp v135, -v148, v127 row_newbcast:13 row_mask:0xf bank_mask:0xf
	v_fmac_f32_dpp v136, -v148, v128 row_newbcast:14 row_mask:0xf bank_mask:0xf
	v_fmac_f32_dpp v137, -v148, v129 row_newbcast:15 row_mask:0xf bank_mask:0xf
	v_fmac_f32_dpp v134, -v148, v126 row_newbcast:12 row_mask:0xf bank_mask:0xf
	v_cndmask_b32_e64 v130, 0, 1.0, vcc
	v_add_f32_e32 v20, v134, v135
	v_add_f32_e32 v21, v136, v137
	v_add_f32_e32 v113, v20, v21
	ds_read_b32 v148, v138 offset:7568
	ds_read_b32 v149, v138 offset:7632
	s_waitcnt lgkmcnt(4)
	v_cmp_eq_u32_e32 vcc, 45, v139
	v_fmac_f32_dpp v130, -v144, v114 row_newbcast:4 row_mask:0xf bank_mask:0xf
	v_mul_f32_dpp v131, -v144, v115 row_newbcast:5 row_mask:0xf bank_mask:0xf
	v_mul_f32_dpp v132, -v144, v116 row_newbcast:6 row_mask:0xf bank_mask:0xf
	v_mul_f32_dpp v133, -v144, v113 row_newbcast:3 row_mask:0xf bank_mask:0xf
	v_fmac_f32_dpp v130, -v144, v118 row_newbcast:8 row_mask:0xf bank_mask:0xf
	v_fmac_f32_dpp v131, -v144, v119 row_newbcast:9 row_mask:0xf bank_mask:0xf
	v_fmac_f32_dpp v132, -v144, v120 row_newbcast:10 row_mask:0xf bank_mask:0xf
	v_fmac_f32_dpp v133, -v144, v117 row_newbcast:7 row_mask:0xf bank_mask:0xf
	v_fmac_f32_dpp v130, -v144, v122 row_newbcast:12 row_mask:0xf bank_mask:0xf
	v_fmac_f32_dpp v131, -v144, v123 row_newbcast:13 row_mask:0xf bank_mask:0xf
	v_fmac_f32_dpp v132, -v144, v124 row_newbcast:14 row_mask:0xf bank_mask:0xf
	v_fmac_f32_dpp v133, -v144, v121 row_newbcast:11 row_mask:0xf bank_mask:0xf
	v_fmac_f32_dpp v130, -v145, v126 row_newbcast:0 row_mask:0xf bank_mask:0xf
	v_fmac_f32_dpp v131, -v145, v127 row_newbcast:1 row_mask:0xf bank_mask:0xf
	v_fmac_f32_dpp v132, -v145, v128 row_newbcast:2 row_mask:0xf bank_mask:0xf
	v_fmac_f32_dpp v133, -v144, v125 row_newbcast:15 row_mask:0xf bank_mask:0xf
	s_nop 1
	v_fmac_f32_dpp v133, -v145, v129 row_newbcast:3 row_mask:0xf bank_mask:0xf
	v_cndmask_b32_e64 v134, 0, 1.0, vcc
	v_add_f32_e32 v20, v130, v131
	v_add_f32_e32 v21, v132, v133
	v_add_f32_e32 v112, v20, v21
	ds_read_b32 v144, v138 offset:7488
	ds_read_b32 v145, v138 offset:7552
	s_waitcnt lgkmcnt(4)
	v_cmp_eq_u32_e32 vcc, 44, v139
	v_mul_f32_dpp v137, -v140, v113 row_newbcast:3 row_mask:0xf bank_mask:0xf
	v_fmac_f32_dpp v134, -v140, v114 row_newbcast:4 row_mask:0xf bank_mask:0xf
	v_mul_f32_dpp v135, -v140, v115 row_newbcast:5 row_mask:0xf bank_mask:0xf
	v_mul_f32_dpp v136, -v140, v112 row_newbcast:2 row_mask:0xf bank_mask:0xf
	v_fmac_f32_dpp v137, -v140, v117 row_newbcast:7 row_mask:0xf bank_mask:0xf
	v_fmac_f32_dpp v134, -v140, v118 row_newbcast:8 row_mask:0xf bank_mask:0xf
	v_fmac_f32_dpp v135, -v140, v119 row_newbcast:9 row_mask:0xf bank_mask:0xf
	v_fmac_f32_dpp v136, -v140, v116 row_newbcast:6 row_mask:0xf bank_mask:0xf
	v_fmac_f32_dpp v137, -v140, v121 row_newbcast:11 row_mask:0xf bank_mask:0xf
	v_fmac_f32_dpp v134, -v140, v122 row_newbcast:12 row_mask:0xf bank_mask:0xf
	v_fmac_f32_dpp v135, -v140, v123 row_newbcast:13 row_mask:0xf bank_mask:0xf
	v_fmac_f32_dpp v136, -v140, v120 row_newbcast:10 row_mask:0xf bank_mask:0xf
	v_fmac_f32_dpp v137, -v140, v125 row_newbcast:15 row_mask:0xf bank_mask:0xf
	v_fmac_f32_dpp v134, -v141, v126 row_newbcast:0 row_mask:0xf bank_mask:0xf
	v_fmac_f32_dpp v135, -v141, v127 row_newbcast:1 row_mask:0xf bank_mask:0xf
	v_fmac_f32_dpp v136, -v140, v124 row_newbcast:14 row_mask:0xf bank_mask:0xf
	v_fmac_f32_dpp v137, -v141, v129 row_newbcast:3 row_mask:0xf bank_mask:0xf
	s_nop 0
	v_fmac_f32_dpp v136, -v141, v128 row_newbcast:2 row_mask:0xf bank_mask:0xf
	v_cndmask_b32_e64 v130, 0, 1.0, vcc
	v_add_f32_e32 v20, v134, v135
	v_add_f32_e32 v21, v136, v137
	v_add_f32_e32 v111, v20, v21
	ds_read_b32 v140, v138 offset:7392
	ds_read_b32 v141, v138 offset:7456
	s_waitcnt lgkmcnt(4)
	v_cmp_eq_u32_e32 vcc, 43, v139
	v_mul_f32_dpp v132, -v148, v112 row_newbcast:2 row_mask:0xf bank_mask:0xf
	v_mul_f32_dpp v133, -v148, v113 row_newbcast:3 row_mask:0xf bank_mask:0xf
	v_fmac_f32_dpp v130, -v148, v114 row_newbcast:4 row_mask:0xf bank_mask:0xf
	v_mul_f32_dpp v131, -v148, v111 row_newbcast:1 row_mask:0xf bank_mask:0xf
	v_fmac_f32_dpp v132, -v148, v116 row_newbcast:6 row_mask:0xf bank_mask:0xf
	v_fmac_f32_dpp v133, -v148, v117 row_newbcast:7 row_mask:0xf bank_mask:0xf
	v_fmac_f32_dpp v130, -v148, v118 row_newbcast:8 row_mask:0xf bank_mask:0xf
	v_fmac_f32_dpp v131, -v148, v115 row_newbcast:5 row_mask:0xf bank_mask:0xf
	v_fmac_f32_dpp v132, -v148, v120 row_newbcast:10 row_mask:0xf bank_mask:0xf
	v_fmac_f32_dpp v133, -v148, v121 row_newbcast:11 row_mask:0xf bank_mask:0xf
	v_fmac_f32_dpp v130, -v148, v122 row_newbcast:12 row_mask:0xf bank_mask:0xf
	v_fmac_f32_dpp v131, -v148, v119 row_newbcast:9 row_mask:0xf bank_mask:0xf
	v_fmac_f32_dpp v132, -v148, v124 row_newbcast:14 row_mask:0xf bank_mask:0xf
	v_fmac_f32_dpp v133, -v148, v125 row_newbcast:15 row_mask:0xf bank_mask:0xf
	v_fmac_f32_dpp v130, -v149, v126 row_newbcast:0 row_mask:0xf bank_mask:0xf
	v_fmac_f32_dpp v131, -v148, v123 row_newbcast:13 row_mask:0xf bank_mask:0xf
	v_fmac_f32_dpp v132, -v149, v128 row_newbcast:2 row_mask:0xf bank_mask:0xf
	v_fmac_f32_dpp v133, -v149, v129 row_newbcast:3 row_mask:0xf bank_mask:0xf
	v_fmac_f32_dpp v131, -v149, v127 row_newbcast:1 row_mask:0xf bank_mask:0xf
	v_cndmask_b32_e64 v134, 0, 1.0, vcc
	v_add_f32_e32 v20, v130, v131
	v_add_f32_e32 v21, v132, v133
	v_add_f32_e32 v110, v20, v21
	ds_read_b32 v148, v138 offset:7296
	ds_read_b32 v149, v138 offset:7360
	s_waitcnt lgkmcnt(4)
	v_cmp_eq_u32_e32 vcc, 42, v139
	v_mul_f32_dpp v135, -v144, v111 row_newbcast:1 row_mask:0xf bank_mask:0xf
	v_mul_f32_dpp v136, -v144, v112 row_newbcast:2 row_mask:0xf bank_mask:0xf
	v_mul_f32_dpp v137, -v144, v113 row_newbcast:3 row_mask:0xf bank_mask:0xf
	v_fmac_f32_dpp v134, -v144, v110 row_newbcast:0 row_mask:0xf bank_mask:0xf
	v_fmac_f32_dpp v135, -v144, v115 row_newbcast:5 row_mask:0xf bank_mask:0xf
	v_fmac_f32_dpp v136, -v144, v116 row_newbcast:6 row_mask:0xf bank_mask:0xf
	v_fmac_f32_dpp v137, -v144, v117 row_newbcast:7 row_mask:0xf bank_mask:0xf
	v_fmac_f32_dpp v134, -v144, v114 row_newbcast:4 row_mask:0xf bank_mask:0xf
	v_fmac_f32_dpp v135, -v144, v119 row_newbcast:9 row_mask:0xf bank_mask:0xf
	v_fmac_f32_dpp v136, -v144, v120 row_newbcast:10 row_mask:0xf bank_mask:0xf
	v_fmac_f32_dpp v137, -v144, v121 row_newbcast:11 row_mask:0xf bank_mask:0xf
	v_fmac_f32_dpp v134, -v144, v118 row_newbcast:8 row_mask:0xf bank_mask:0xf
	v_fmac_f32_dpp v135, -v144, v123 row_newbcast:13 row_mask:0xf bank_mask:0xf
	v_fmac_f32_dpp v136, -v144, v124 row_newbcast:14 row_mask:0xf bank_mask:0xf
	v_fmac_f32_dpp v137, -v144, v125 row_newbcast:15 row_mask:0xf bank_mask:0xf
	v_fmac_f32_dpp v134, -v144, v122 row_newbcast:12 row_mask:0xf bank_mask:0xf
	v_fmac_f32_dpp v135, -v145, v127 row_newbcast:1 row_mask:0xf bank_mask:0xf
	v_fmac_f32_dpp v136, -v145, v128 row_newbcast:2 row_mask:0xf bank_mask:0xf
	v_fmac_f32_dpp v137, -v145, v129 row_newbcast:3 row_mask:0xf bank_mask:0xf
	v_fmac_f32_dpp v134, -v145, v126 row_newbcast:0 row_mask:0xf bank_mask:0xf
	v_cndmask_b32_e64 v130, 0, 1.0, vcc
	v_add_f32_e32 v20, v134, v135
	v_add_f32_e32 v21, v136, v137
	v_add_f32_e32 v109, v20, v21
	ds_read_b32 v144, v138 offset:7200
	ds_read_b32 v145, v138 offset:7264
	s_waitcnt lgkmcnt(4)
	v_cmp_eq_u32_e32 vcc, 41, v139
	v_fmac_f32_dpp v130, -v140, v110 row_newbcast:4 row_mask:0xf bank_mask:0xf
	v_mul_f32_dpp v131, -v140, v111 row_newbcast:5 row_mask:0xf bank_mask:0xf
	v_mul_f32_dpp v132, -v140, v112 row_newbcast:6 row_mask:0xf bank_mask:0xf
	v_mul_f32_dpp v133, -v140, v109 row_newbcast:3 row_mask:0xf bank_mask:0xf
	v_fmac_f32_dpp v130, -v140, v114 row_newbcast:8 row_mask:0xf bank_mask:0xf
	v_fmac_f32_dpp v131, -v140, v115 row_newbcast:9 row_mask:0xf bank_mask:0xf
	v_fmac_f32_dpp v132, -v140, v116 row_newbcast:10 row_mask:0xf bank_mask:0xf
	v_fmac_f32_dpp v133, -v140, v113 row_newbcast:7 row_mask:0xf bank_mask:0xf
	v_fmac_f32_dpp v130, -v140, v118 row_newbcast:12 row_mask:0xf bank_mask:0xf
	v_fmac_f32_dpp v131, -v140, v119 row_newbcast:13 row_mask:0xf bank_mask:0xf
	v_fmac_f32_dpp v132, -v140, v120 row_newbcast:14 row_mask:0xf bank_mask:0xf
	v_fmac_f32_dpp v133, -v140, v117 row_newbcast:11 row_mask:0xf bank_mask:0xf
	v_fmac_f32_dpp v130, -v141, v122 row_newbcast:0 row_mask:0xf bank_mask:0xf
	v_fmac_f32_dpp v131, -v141, v123 row_newbcast:1 row_mask:0xf bank_mask:0xf
	v_fmac_f32_dpp v132, -v141, v124 row_newbcast:2 row_mask:0xf bank_mask:0xf
	v_fmac_f32_dpp v133, -v140, v121 row_newbcast:15 row_mask:0xf bank_mask:0xf
	v_fmac_f32_dpp v130, -v141, v126 row_newbcast:4 row_mask:0xf bank_mask:0xf
	v_fmac_f32_dpp v131, -v141, v127 row_newbcast:5 row_mask:0xf bank_mask:0xf
	v_fmac_f32_dpp v132, -v141, v128 row_newbcast:6 row_mask:0xf bank_mask:0xf
	v_fmac_f32_dpp v133, -v141, v125 row_newbcast:3 row_mask:0xf bank_mask:0xf
	s_nop 1
	v_fmac_f32_dpp v133, -v141, v129 row_newbcast:7 row_mask:0xf bank_mask:0xf
	v_cndmask_b32_e64 v134, 0, 1.0, vcc
	v_add_f32_e32 v20, v130, v131
	v_add_f32_e32 v21, v132, v133
	v_add_f32_e32 v108, v20, v21
	ds_read_b32 v140, v138 offset:7104
	ds_read_b32 v141, v138 offset:7168
	s_waitcnt lgkmcnt(4)
	v_cmp_eq_u32_e32 vcc, 40, v139
	v_mul_f32_dpp v137, -v148, v109 row_newbcast:3 row_mask:0xf bank_mask:0xf
	v_fmac_f32_dpp v134, -v148, v110 row_newbcast:4 row_mask:0xf bank_mask:0xf
	v_mul_f32_dpp v135, -v148, v111 row_newbcast:5 row_mask:0xf bank_mask:0xf
	v_mul_f32_dpp v136, -v148, v108 row_newbcast:2 row_mask:0xf bank_mask:0xf
	v_fmac_f32_dpp v137, -v148, v113 row_newbcast:7 row_mask:0xf bank_mask:0xf
	v_fmac_f32_dpp v134, -v148, v114 row_newbcast:8 row_mask:0xf bank_mask:0xf
	v_fmac_f32_dpp v135, -v148, v115 row_newbcast:9 row_mask:0xf bank_mask:0xf
	v_fmac_f32_dpp v136, -v148, v112 row_newbcast:6 row_mask:0xf bank_mask:0xf
	v_fmac_f32_dpp v137, -v148, v117 row_newbcast:11 row_mask:0xf bank_mask:0xf
	v_fmac_f32_dpp v134, -v148, v118 row_newbcast:12 row_mask:0xf bank_mask:0xf
	v_fmac_f32_dpp v135, -v148, v119 row_newbcast:13 row_mask:0xf bank_mask:0xf
	v_fmac_f32_dpp v136, -v148, v116 row_newbcast:10 row_mask:0xf bank_mask:0xf
	v_fmac_f32_dpp v137, -v148, v121 row_newbcast:15 row_mask:0xf bank_mask:0xf
	v_fmac_f32_dpp v134, -v149, v122 row_newbcast:0 row_mask:0xf bank_mask:0xf
	v_fmac_f32_dpp v135, -v149, v123 row_newbcast:1 row_mask:0xf bank_mask:0xf
	v_fmac_f32_dpp v136, -v148, v120 row_newbcast:14 row_mask:0xf bank_mask:0xf
	v_fmac_f32_dpp v137, -v149, v125 row_newbcast:3 row_mask:0xf bank_mask:0xf
	v_fmac_f32_dpp v134, -v149, v126 row_newbcast:4 row_mask:0xf bank_mask:0xf
	v_fmac_f32_dpp v135, -v149, v127 row_newbcast:5 row_mask:0xf bank_mask:0xf
	v_fmac_f32_dpp v136, -v149, v124 row_newbcast:2 row_mask:0xf bank_mask:0xf
	v_fmac_f32_dpp v137, -v149, v129 row_newbcast:7 row_mask:0xf bank_mask:0xf
	s_nop 0
	v_fmac_f32_dpp v136, -v149, v128 row_newbcast:6 row_mask:0xf bank_mask:0xf
	v_cndmask_b32_e64 v130, 0, 1.0, vcc
	v_add_f32_e32 v20, v134, v135
	v_add_f32_e32 v21, v136, v137
	v_add_f32_e32 v107, v20, v21
	ds_read_b32 v148, v138 offset:6992
	ds_read_b32 v149, v138 offset:7056
	s_waitcnt lgkmcnt(4)
	v_cmp_eq_u32_e32 vcc, 39, v139
	v_mul_f32_dpp v132, -v144, v108 row_newbcast:2 row_mask:0xf bank_mask:0xf
	v_mul_f32_dpp v133, -v144, v109 row_newbcast:3 row_mask:0xf bank_mask:0xf
	v_fmac_f32_dpp v130, -v144, v110 row_newbcast:4 row_mask:0xf bank_mask:0xf
	v_mul_f32_dpp v131, -v144, v107 row_newbcast:1 row_mask:0xf bank_mask:0xf
	v_fmac_f32_dpp v132, -v144, v112 row_newbcast:6 row_mask:0xf bank_mask:0xf
	v_fmac_f32_dpp v133, -v144, v113 row_newbcast:7 row_mask:0xf bank_mask:0xf
	v_fmac_f32_dpp v130, -v144, v114 row_newbcast:8 row_mask:0xf bank_mask:0xf
	v_fmac_f32_dpp v131, -v144, v111 row_newbcast:5 row_mask:0xf bank_mask:0xf
	v_fmac_f32_dpp v132, -v144, v116 row_newbcast:10 row_mask:0xf bank_mask:0xf
	v_fmac_f32_dpp v133, -v144, v117 row_newbcast:11 row_mask:0xf bank_mask:0xf
	v_fmac_f32_dpp v130, -v144, v118 row_newbcast:12 row_mask:0xf bank_mask:0xf
	v_fmac_f32_dpp v131, -v144, v115 row_newbcast:9 row_mask:0xf bank_mask:0xf
	v_fmac_f32_dpp v132, -v144, v120 row_newbcast:14 row_mask:0xf bank_mask:0xf
	v_fmac_f32_dpp v133, -v144, v121 row_newbcast:15 row_mask:0xf bank_mask:0xf
	v_fmac_f32_dpp v130, -v145, v122 row_newbcast:0 row_mask:0xf bank_mask:0xf
	v_fmac_f32_dpp v131, -v144, v119 row_newbcast:13 row_mask:0xf bank_mask:0xf
	v_fmac_f32_dpp v132, -v145, v124 row_newbcast:2 row_mask:0xf bank_mask:0xf
	v_fmac_f32_dpp v133, -v145, v125 row_newbcast:3 row_mask:0xf bank_mask:0xf
	v_fmac_f32_dpp v130, -v145, v126 row_newbcast:4 row_mask:0xf bank_mask:0xf
	v_fmac_f32_dpp v131, -v145, v123 row_newbcast:1 row_mask:0xf bank_mask:0xf
	v_fmac_f32_dpp v132, -v145, v128 row_newbcast:6 row_mask:0xf bank_mask:0xf
	v_fmac_f32_dpp v133, -v145, v129 row_newbcast:7 row_mask:0xf bank_mask:0xf
	v_fmac_f32_dpp v131, -v145, v127 row_newbcast:5 row_mask:0xf bank_mask:0xf
	v_cndmask_b32_e64 v134, 0, 1.0, vcc
	v_add_f32_e32 v20, v130, v131
	v_add_f32_e32 v21, v132, v133
	v_add_f32_e32 v106, v20, v21
	ds_read_b32 v144, v138 offset:6880
	ds_read_b32 v145, v138 offset:6944
	s_waitcnt lgkmcnt(4)
	v_cmp_eq_u32_e32 vcc, 38, v139
	v_mul_f32_dpp v135, -v140, v107 row_newbcast:1 row_mask:0xf bank_mask:0xf
	v_mul_f32_dpp v136, -v140, v108 row_newbcast:2 row_mask:0xf bank_mask:0xf
	v_mul_f32_dpp v137, -v140, v109 row_newbcast:3 row_mask:0xf bank_mask:0xf
	v_fmac_f32_dpp v134, -v140, v106 row_newbcast:0 row_mask:0xf bank_mask:0xf
	v_fmac_f32_dpp v135, -v140, v111 row_newbcast:5 row_mask:0xf bank_mask:0xf
	v_fmac_f32_dpp v136, -v140, v112 row_newbcast:6 row_mask:0xf bank_mask:0xf
	v_fmac_f32_dpp v137, -v140, v113 row_newbcast:7 row_mask:0xf bank_mask:0xf
	v_fmac_f32_dpp v134, -v140, v110 row_newbcast:4 row_mask:0xf bank_mask:0xf
	v_fmac_f32_dpp v135, -v140, v115 row_newbcast:9 row_mask:0xf bank_mask:0xf
	v_fmac_f32_dpp v136, -v140, v116 row_newbcast:10 row_mask:0xf bank_mask:0xf
	v_fmac_f32_dpp v137, -v140, v117 row_newbcast:11 row_mask:0xf bank_mask:0xf
	v_fmac_f32_dpp v134, -v140, v114 row_newbcast:8 row_mask:0xf bank_mask:0xf
	v_fmac_f32_dpp v135, -v140, v119 row_newbcast:13 row_mask:0xf bank_mask:0xf
	v_fmac_f32_dpp v136, -v140, v120 row_newbcast:14 row_mask:0xf bank_mask:0xf
	v_fmac_f32_dpp v137, -v140, v121 row_newbcast:15 row_mask:0xf bank_mask:0xf
	v_fmac_f32_dpp v134, -v140, v118 row_newbcast:12 row_mask:0xf bank_mask:0xf
	v_fmac_f32_dpp v135, -v141, v123 row_newbcast:1 row_mask:0xf bank_mask:0xf
	v_fmac_f32_dpp v136, -v141, v124 row_newbcast:2 row_mask:0xf bank_mask:0xf
	v_fmac_f32_dpp v137, -v141, v125 row_newbcast:3 row_mask:0xf bank_mask:0xf
	v_fmac_f32_dpp v134, -v141, v122 row_newbcast:0 row_mask:0xf bank_mask:0xf
	v_fmac_f32_dpp v135, -v141, v127 row_newbcast:5 row_mask:0xf bank_mask:0xf
	v_fmac_f32_dpp v136, -v141, v128 row_newbcast:6 row_mask:0xf bank_mask:0xf
	v_fmac_f32_dpp v137, -v141, v129 row_newbcast:7 row_mask:0xf bank_mask:0xf
	v_fmac_f32_dpp v134, -v141, v126 row_newbcast:4 row_mask:0xf bank_mask:0xf
	v_cndmask_b32_e64 v130, 0, 1.0, vcc
	v_add_f32_e32 v20, v134, v135
	v_add_f32_e32 v21, v136, v137
	v_add_f32_e32 v105, v20, v21
	ds_read_b32 v140, v138 offset:6768
	ds_read_b32 v141, v138 offset:6832
	s_waitcnt lgkmcnt(4)
	v_cmp_eq_u32_e32 vcc, 37, v139
	v_fmac_f32_dpp v130, -v148, v106 row_newbcast:4 row_mask:0xf bank_mask:0xf
	v_mul_f32_dpp v131, -v148, v107 row_newbcast:5 row_mask:0xf bank_mask:0xf
	v_mul_f32_dpp v132, -v148, v108 row_newbcast:6 row_mask:0xf bank_mask:0xf
	v_mul_f32_dpp v133, -v148, v105 row_newbcast:3 row_mask:0xf bank_mask:0xf
	v_fmac_f32_dpp v130, -v148, v110 row_newbcast:8 row_mask:0xf bank_mask:0xf
	v_fmac_f32_dpp v131, -v148, v111 row_newbcast:9 row_mask:0xf bank_mask:0xf
	v_fmac_f32_dpp v132, -v148, v112 row_newbcast:10 row_mask:0xf bank_mask:0xf
	v_fmac_f32_dpp v133, -v148, v109 row_newbcast:7 row_mask:0xf bank_mask:0xf
	v_fmac_f32_dpp v130, -v148, v114 row_newbcast:12 row_mask:0xf bank_mask:0xf
	v_fmac_f32_dpp v131, -v148, v115 row_newbcast:13 row_mask:0xf bank_mask:0xf
	v_fmac_f32_dpp v132, -v148, v116 row_newbcast:14 row_mask:0xf bank_mask:0xf
	v_fmac_f32_dpp v133, -v148, v113 row_newbcast:11 row_mask:0xf bank_mask:0xf
	v_fmac_f32_dpp v130, -v149, v118 row_newbcast:0 row_mask:0xf bank_mask:0xf
	v_fmac_f32_dpp v131, -v149, v119 row_newbcast:1 row_mask:0xf bank_mask:0xf
	v_fmac_f32_dpp v132, -v149, v120 row_newbcast:2 row_mask:0xf bank_mask:0xf
	v_fmac_f32_dpp v133, -v148, v117 row_newbcast:15 row_mask:0xf bank_mask:0xf
	v_fmac_f32_dpp v130, -v149, v122 row_newbcast:4 row_mask:0xf bank_mask:0xf
	v_fmac_f32_dpp v131, -v149, v123 row_newbcast:5 row_mask:0xf bank_mask:0xf
	v_fmac_f32_dpp v132, -v149, v124 row_newbcast:6 row_mask:0xf bank_mask:0xf
	v_fmac_f32_dpp v133, -v149, v121 row_newbcast:3 row_mask:0xf bank_mask:0xf
	v_fmac_f32_dpp v130, -v149, v126 row_newbcast:8 row_mask:0xf bank_mask:0xf
	v_fmac_f32_dpp v131, -v149, v127 row_newbcast:9 row_mask:0xf bank_mask:0xf
	v_fmac_f32_dpp v132, -v149, v128 row_newbcast:10 row_mask:0xf bank_mask:0xf
	v_fmac_f32_dpp v133, -v149, v125 row_newbcast:7 row_mask:0xf bank_mask:0xf
	s_nop 1
	v_fmac_f32_dpp v133, -v149, v129 row_newbcast:11 row_mask:0xf bank_mask:0xf
	v_cndmask_b32_e64 v134, 0, 1.0, vcc
	v_add_f32_e32 v20, v130, v131
	v_add_f32_e32 v21, v132, v133
	v_add_f32_e32 v104, v20, v21
	ds_read_b32 v148, v138 offset:6656
	ds_read_b32 v149, v138 offset:6720
	s_waitcnt lgkmcnt(4)
	v_cmp_eq_u32_e32 vcc, 36, v139
	v_mul_f32_dpp v137, -v144, v105 row_newbcast:3 row_mask:0xf bank_mask:0xf
	v_fmac_f32_dpp v134, -v144, v106 row_newbcast:4 row_mask:0xf bank_mask:0xf
	v_mul_f32_dpp v135, -v144, v107 row_newbcast:5 row_mask:0xf bank_mask:0xf
	v_mul_f32_dpp v136, -v144, v104 row_newbcast:2 row_mask:0xf bank_mask:0xf
	v_fmac_f32_dpp v137, -v144, v109 row_newbcast:7 row_mask:0xf bank_mask:0xf
	v_fmac_f32_dpp v134, -v144, v110 row_newbcast:8 row_mask:0xf bank_mask:0xf
	v_fmac_f32_dpp v135, -v144, v111 row_newbcast:9 row_mask:0xf bank_mask:0xf
	v_fmac_f32_dpp v136, -v144, v108 row_newbcast:6 row_mask:0xf bank_mask:0xf
	v_fmac_f32_dpp v137, -v144, v113 row_newbcast:11 row_mask:0xf bank_mask:0xf
	v_fmac_f32_dpp v134, -v144, v114 row_newbcast:12 row_mask:0xf bank_mask:0xf
	v_fmac_f32_dpp v135, -v144, v115 row_newbcast:13 row_mask:0xf bank_mask:0xf
	v_fmac_f32_dpp v136, -v144, v112 row_newbcast:10 row_mask:0xf bank_mask:0xf
	v_fmac_f32_dpp v137, -v144, v117 row_newbcast:15 row_mask:0xf bank_mask:0xf
	v_fmac_f32_dpp v134, -v145, v118 row_newbcast:0 row_mask:0xf bank_mask:0xf
	v_fmac_f32_dpp v135, -v145, v119 row_newbcast:1 row_mask:0xf bank_mask:0xf
	v_fmac_f32_dpp v136, -v144, v116 row_newbcast:14 row_mask:0xf bank_mask:0xf
	v_fmac_f32_dpp v137, -v145, v121 row_newbcast:3 row_mask:0xf bank_mask:0xf
	v_fmac_f32_dpp v134, -v145, v122 row_newbcast:4 row_mask:0xf bank_mask:0xf
	v_fmac_f32_dpp v135, -v145, v123 row_newbcast:5 row_mask:0xf bank_mask:0xf
	v_fmac_f32_dpp v136, -v145, v120 row_newbcast:2 row_mask:0xf bank_mask:0xf
	v_fmac_f32_dpp v137, -v145, v125 row_newbcast:7 row_mask:0xf bank_mask:0xf
	v_fmac_f32_dpp v134, -v145, v126 row_newbcast:8 row_mask:0xf bank_mask:0xf
	v_fmac_f32_dpp v135, -v145, v127 row_newbcast:9 row_mask:0xf bank_mask:0xf
	v_fmac_f32_dpp v136, -v145, v124 row_newbcast:6 row_mask:0xf bank_mask:0xf
	v_fmac_f32_dpp v137, -v145, v129 row_newbcast:11 row_mask:0xf bank_mask:0xf
	s_nop 0
	v_fmac_f32_dpp v136, -v145, v128 row_newbcast:10 row_mask:0xf bank_mask:0xf
	v_cndmask_b32_e64 v130, 0, 1.0, vcc
	v_add_f32_e32 v20, v134, v135
	v_add_f32_e32 v21, v136, v137
	v_add_f32_e32 v103, v20, v21
	ds_read_b32 v144, v138 offset:6528
	ds_read_b32 v145, v138 offset:6592
	s_waitcnt lgkmcnt(4)
	v_cmp_eq_u32_e32 vcc, 35, v139
	v_mul_f32_dpp v132, -v140, v104 row_newbcast:2 row_mask:0xf bank_mask:0xf
	v_mul_f32_dpp v133, -v140, v105 row_newbcast:3 row_mask:0xf bank_mask:0xf
	v_fmac_f32_dpp v130, -v140, v106 row_newbcast:4 row_mask:0xf bank_mask:0xf
	v_mul_f32_dpp v131, -v140, v103 row_newbcast:1 row_mask:0xf bank_mask:0xf
	v_fmac_f32_dpp v132, -v140, v108 row_newbcast:6 row_mask:0xf bank_mask:0xf
	v_fmac_f32_dpp v133, -v140, v109 row_newbcast:7 row_mask:0xf bank_mask:0xf
	v_fmac_f32_dpp v130, -v140, v110 row_newbcast:8 row_mask:0xf bank_mask:0xf
	v_fmac_f32_dpp v131, -v140, v107 row_newbcast:5 row_mask:0xf bank_mask:0xf
	v_fmac_f32_dpp v132, -v140, v112 row_newbcast:10 row_mask:0xf bank_mask:0xf
	v_fmac_f32_dpp v133, -v140, v113 row_newbcast:11 row_mask:0xf bank_mask:0xf
	v_fmac_f32_dpp v130, -v140, v114 row_newbcast:12 row_mask:0xf bank_mask:0xf
	v_fmac_f32_dpp v131, -v140, v111 row_newbcast:9 row_mask:0xf bank_mask:0xf
	v_fmac_f32_dpp v132, -v140, v116 row_newbcast:14 row_mask:0xf bank_mask:0xf
	v_fmac_f32_dpp v133, -v140, v117 row_newbcast:15 row_mask:0xf bank_mask:0xf
	v_fmac_f32_dpp v130, -v141, v118 row_newbcast:0 row_mask:0xf bank_mask:0xf
	v_fmac_f32_dpp v131, -v140, v115 row_newbcast:13 row_mask:0xf bank_mask:0xf
	v_fmac_f32_dpp v132, -v141, v120 row_newbcast:2 row_mask:0xf bank_mask:0xf
	v_fmac_f32_dpp v133, -v141, v121 row_newbcast:3 row_mask:0xf bank_mask:0xf
	v_fmac_f32_dpp v130, -v141, v122 row_newbcast:4 row_mask:0xf bank_mask:0xf
	v_fmac_f32_dpp v131, -v141, v119 row_newbcast:1 row_mask:0xf bank_mask:0xf
	v_fmac_f32_dpp v132, -v141, v124 row_newbcast:6 row_mask:0xf bank_mask:0xf
	v_fmac_f32_dpp v133, -v141, v125 row_newbcast:7 row_mask:0xf bank_mask:0xf
	v_fmac_f32_dpp v130, -v141, v126 row_newbcast:8 row_mask:0xf bank_mask:0xf
	v_fmac_f32_dpp v131, -v141, v123 row_newbcast:5 row_mask:0xf bank_mask:0xf
	v_fmac_f32_dpp v132, -v141, v128 row_newbcast:10 row_mask:0xf bank_mask:0xf
	v_fmac_f32_dpp v133, -v141, v129 row_newbcast:11 row_mask:0xf bank_mask:0xf
	v_fmac_f32_dpp v131, -v141, v127 row_newbcast:9 row_mask:0xf bank_mask:0xf
	v_cndmask_b32_e64 v134, 0, 1.0, vcc
	v_add_f32_e32 v20, v130, v131
	v_add_f32_e32 v21, v132, v133
	v_add_f32_e32 v102, v20, v21
	ds_read_b32 v140, v138 offset:6400
	ds_read_b32 v141, v138 offset:6464
	s_waitcnt lgkmcnt(4)
	v_cmp_eq_u32_e32 vcc, 34, v139
	v_mul_f32_dpp v135, -v148, v103 row_newbcast:1 row_mask:0xf bank_mask:0xf
	v_mul_f32_dpp v136, -v148, v104 row_newbcast:2 row_mask:0xf bank_mask:0xf
	v_mul_f32_dpp v137, -v148, v105 row_newbcast:3 row_mask:0xf bank_mask:0xf
	v_fmac_f32_dpp v134, -v148, v102 row_newbcast:0 row_mask:0xf bank_mask:0xf
	v_fmac_f32_dpp v135, -v148, v107 row_newbcast:5 row_mask:0xf bank_mask:0xf
	v_fmac_f32_dpp v136, -v148, v108 row_newbcast:6 row_mask:0xf bank_mask:0xf
	v_fmac_f32_dpp v137, -v148, v109 row_newbcast:7 row_mask:0xf bank_mask:0xf
	v_fmac_f32_dpp v134, -v148, v106 row_newbcast:4 row_mask:0xf bank_mask:0xf
	v_fmac_f32_dpp v135, -v148, v111 row_newbcast:9 row_mask:0xf bank_mask:0xf
	v_fmac_f32_dpp v136, -v148, v112 row_newbcast:10 row_mask:0xf bank_mask:0xf
	v_fmac_f32_dpp v137, -v148, v113 row_newbcast:11 row_mask:0xf bank_mask:0xf
	v_fmac_f32_dpp v134, -v148, v110 row_newbcast:8 row_mask:0xf bank_mask:0xf
	v_fmac_f32_dpp v135, -v148, v115 row_newbcast:13 row_mask:0xf bank_mask:0xf
	v_fmac_f32_dpp v136, -v148, v116 row_newbcast:14 row_mask:0xf bank_mask:0xf
	v_fmac_f32_dpp v137, -v148, v117 row_newbcast:15 row_mask:0xf bank_mask:0xf
	v_fmac_f32_dpp v134, -v148, v114 row_newbcast:12 row_mask:0xf bank_mask:0xf
	v_fmac_f32_dpp v135, -v149, v119 row_newbcast:1 row_mask:0xf bank_mask:0xf
	v_fmac_f32_dpp v136, -v149, v120 row_newbcast:2 row_mask:0xf bank_mask:0xf
	v_fmac_f32_dpp v137, -v149, v121 row_newbcast:3 row_mask:0xf bank_mask:0xf
	v_fmac_f32_dpp v134, -v149, v118 row_newbcast:0 row_mask:0xf bank_mask:0xf
	v_fmac_f32_dpp v135, -v149, v123 row_newbcast:5 row_mask:0xf bank_mask:0xf
	v_fmac_f32_dpp v136, -v149, v124 row_newbcast:6 row_mask:0xf bank_mask:0xf
	v_fmac_f32_dpp v137, -v149, v125 row_newbcast:7 row_mask:0xf bank_mask:0xf
	v_fmac_f32_dpp v134, -v149, v122 row_newbcast:4 row_mask:0xf bank_mask:0xf
	v_fmac_f32_dpp v135, -v149, v127 row_newbcast:9 row_mask:0xf bank_mask:0xf
	v_fmac_f32_dpp v136, -v149, v128 row_newbcast:10 row_mask:0xf bank_mask:0xf
	v_fmac_f32_dpp v137, -v149, v129 row_newbcast:11 row_mask:0xf bank_mask:0xf
	v_fmac_f32_dpp v134, -v149, v126 row_newbcast:8 row_mask:0xf bank_mask:0xf
	v_cndmask_b32_e64 v130, 0, 1.0, vcc
	v_add_f32_e32 v20, v134, v135
	v_add_f32_e32 v21, v136, v137
	v_add_f32_e32 v101, v20, v21
	ds_read_b32 v148, v138 offset:6272
	ds_read_b32 v149, v138 offset:6336
	s_waitcnt lgkmcnt(4)
	v_cmp_eq_u32_e32 vcc, 33, v139
	v_fmac_f32_dpp v130, -v144, v102 row_newbcast:4 row_mask:0xf bank_mask:0xf
	v_mul_f32_dpp v131, -v144, v103 row_newbcast:5 row_mask:0xf bank_mask:0xf
	v_mul_f32_dpp v132, -v144, v104 row_newbcast:6 row_mask:0xf bank_mask:0xf
	v_mul_f32_dpp v133, -v144, v101 row_newbcast:3 row_mask:0xf bank_mask:0xf
	v_fmac_f32_dpp v130, -v144, v106 row_newbcast:8 row_mask:0xf bank_mask:0xf
	v_fmac_f32_dpp v131, -v144, v107 row_newbcast:9 row_mask:0xf bank_mask:0xf
	v_fmac_f32_dpp v132, -v144, v108 row_newbcast:10 row_mask:0xf bank_mask:0xf
	v_fmac_f32_dpp v133, -v144, v105 row_newbcast:7 row_mask:0xf bank_mask:0xf
	v_fmac_f32_dpp v130, -v144, v110 row_newbcast:12 row_mask:0xf bank_mask:0xf
	v_fmac_f32_dpp v131, -v144, v111 row_newbcast:13 row_mask:0xf bank_mask:0xf
	v_fmac_f32_dpp v132, -v144, v112 row_newbcast:14 row_mask:0xf bank_mask:0xf
	v_fmac_f32_dpp v133, -v144, v109 row_newbcast:11 row_mask:0xf bank_mask:0xf
	v_fmac_f32_dpp v130, -v145, v114 row_newbcast:0 row_mask:0xf bank_mask:0xf
	v_fmac_f32_dpp v131, -v145, v115 row_newbcast:1 row_mask:0xf bank_mask:0xf
	v_fmac_f32_dpp v132, -v145, v116 row_newbcast:2 row_mask:0xf bank_mask:0xf
	v_fmac_f32_dpp v133, -v144, v113 row_newbcast:15 row_mask:0xf bank_mask:0xf
	v_fmac_f32_dpp v130, -v145, v118 row_newbcast:4 row_mask:0xf bank_mask:0xf
	v_fmac_f32_dpp v131, -v145, v119 row_newbcast:5 row_mask:0xf bank_mask:0xf
	v_fmac_f32_dpp v132, -v145, v120 row_newbcast:6 row_mask:0xf bank_mask:0xf
	v_fmac_f32_dpp v133, -v145, v117 row_newbcast:3 row_mask:0xf bank_mask:0xf
	v_fmac_f32_dpp v130, -v145, v122 row_newbcast:8 row_mask:0xf bank_mask:0xf
	v_fmac_f32_dpp v131, -v145, v123 row_newbcast:9 row_mask:0xf bank_mask:0xf
	v_fmac_f32_dpp v132, -v145, v124 row_newbcast:10 row_mask:0xf bank_mask:0xf
	v_fmac_f32_dpp v133, -v145, v121 row_newbcast:7 row_mask:0xf bank_mask:0xf
	v_fmac_f32_dpp v130, -v145, v126 row_newbcast:12 row_mask:0xf bank_mask:0xf
	v_fmac_f32_dpp v131, -v145, v127 row_newbcast:13 row_mask:0xf bank_mask:0xf
	v_fmac_f32_dpp v132, -v145, v128 row_newbcast:14 row_mask:0xf bank_mask:0xf
	v_fmac_f32_dpp v133, -v145, v125 row_newbcast:11 row_mask:0xf bank_mask:0xf
	s_nop 1
	v_fmac_f32_dpp v133, -v145, v129 row_newbcast:15 row_mask:0xf bank_mask:0xf
	v_cndmask_b32_e64 v134, 0, 1.0, vcc
	v_add_f32_e32 v20, v130, v131
	v_add_f32_e32 v21, v132, v133
	v_add_f32_e32 v100, v20, v21
	s_waitcnt lgkmcnt(2)
	v_cmp_eq_u32_e32 vcc, 32, v139
	v_mul_f32_dpp v137, -v140, v101 row_newbcast:3 row_mask:0xf bank_mask:0xf
	v_fmac_f32_dpp v134, -v140, v102 row_newbcast:4 row_mask:0xf bank_mask:0xf
	v_mul_f32_dpp v135, -v140, v103 row_newbcast:5 row_mask:0xf bank_mask:0xf
	v_mul_f32_dpp v136, -v140, v100 row_newbcast:2 row_mask:0xf bank_mask:0xf
	v_fmac_f32_dpp v137, -v140, v105 row_newbcast:7 row_mask:0xf bank_mask:0xf
	v_fmac_f32_dpp v134, -v140, v106 row_newbcast:8 row_mask:0xf bank_mask:0xf
	v_fmac_f32_dpp v135, -v140, v107 row_newbcast:9 row_mask:0xf bank_mask:0xf
	v_fmac_f32_dpp v136, -v140, v104 row_newbcast:6 row_mask:0xf bank_mask:0xf
	v_fmac_f32_dpp v137, -v140, v109 row_newbcast:11 row_mask:0xf bank_mask:0xf
	v_fmac_f32_dpp v134, -v140, v110 row_newbcast:12 row_mask:0xf bank_mask:0xf
	v_fmac_f32_dpp v135, -v140, v111 row_newbcast:13 row_mask:0xf bank_mask:0xf
	v_fmac_f32_dpp v136, -v140, v108 row_newbcast:10 row_mask:0xf bank_mask:0xf
	v_fmac_f32_dpp v137, -v140, v113 row_newbcast:15 row_mask:0xf bank_mask:0xf
	v_fmac_f32_dpp v134, -v141, v114 row_newbcast:0 row_mask:0xf bank_mask:0xf
	v_fmac_f32_dpp v135, -v141, v115 row_newbcast:1 row_mask:0xf bank_mask:0xf
	v_fmac_f32_dpp v136, -v140, v112 row_newbcast:14 row_mask:0xf bank_mask:0xf
	v_fmac_f32_dpp v137, -v141, v117 row_newbcast:3 row_mask:0xf bank_mask:0xf
	v_fmac_f32_dpp v134, -v141, v118 row_newbcast:4 row_mask:0xf bank_mask:0xf
	v_fmac_f32_dpp v135, -v141, v119 row_newbcast:5 row_mask:0xf bank_mask:0xf
	v_fmac_f32_dpp v136, -v141, v116 row_newbcast:2 row_mask:0xf bank_mask:0xf
	v_fmac_f32_dpp v137, -v141, v121 row_newbcast:7 row_mask:0xf bank_mask:0xf
	v_fmac_f32_dpp v134, -v141, v122 row_newbcast:8 row_mask:0xf bank_mask:0xf
	v_fmac_f32_dpp v135, -v141, v123 row_newbcast:9 row_mask:0xf bank_mask:0xf
	v_fmac_f32_dpp v136, -v141, v120 row_newbcast:6 row_mask:0xf bank_mask:0xf
	v_fmac_f32_dpp v137, -v141, v125 row_newbcast:11 row_mask:0xf bank_mask:0xf
	v_fmac_f32_dpp v134, -v141, v126 row_newbcast:12 row_mask:0xf bank_mask:0xf
	v_fmac_f32_dpp v135, -v141, v127 row_newbcast:13 row_mask:0xf bank_mask:0xf
	v_fmac_f32_dpp v136, -v141, v124 row_newbcast:10 row_mask:0xf bank_mask:0xf
	v_fmac_f32_dpp v137, -v141, v129 row_newbcast:15 row_mask:0xf bank_mask:0xf
	s_nop 0
	v_fmac_f32_dpp v136, -v141, v128 row_newbcast:14 row_mask:0xf bank_mask:0xf
	v_cndmask_b32_e64 v130, 0, 1.0, vcc
	v_add_f32_e32 v20, v134, v135
	v_add_f32_e32 v21, v136, v137
	v_add_f32_e32 v99, v20, v21
	s_waitcnt lgkmcnt(0)
	v_mul_f32_dpp v132, -v148, v100 row_newbcast:2 row_mask:0xf bank_mask:0xf
	v_mul_f32_dpp v133, -v148, v101 row_newbcast:3 row_mask:0xf bank_mask:0xf
	v_fmac_f32_dpp v130, -v148, v102 row_newbcast:4 row_mask:0xf bank_mask:0xf
	v_mul_f32_dpp v131, -v148, v99 row_newbcast:1 row_mask:0xf bank_mask:0xf
	v_fmac_f32_dpp v132, -v148, v104 row_newbcast:6 row_mask:0xf bank_mask:0xf
	v_fmac_f32_dpp v133, -v148, v105 row_newbcast:7 row_mask:0xf bank_mask:0xf
	v_fmac_f32_dpp v130, -v148, v106 row_newbcast:8 row_mask:0xf bank_mask:0xf
	v_fmac_f32_dpp v131, -v148, v103 row_newbcast:5 row_mask:0xf bank_mask:0xf
	v_fmac_f32_dpp v132, -v148, v108 row_newbcast:10 row_mask:0xf bank_mask:0xf
	v_fmac_f32_dpp v133, -v148, v109 row_newbcast:11 row_mask:0xf bank_mask:0xf
	v_fmac_f32_dpp v130, -v148, v110 row_newbcast:12 row_mask:0xf bank_mask:0xf
	v_fmac_f32_dpp v131, -v148, v107 row_newbcast:9 row_mask:0xf bank_mask:0xf
	v_fmac_f32_dpp v132, -v148, v112 row_newbcast:14 row_mask:0xf bank_mask:0xf
	v_fmac_f32_dpp v133, -v148, v113 row_newbcast:15 row_mask:0xf bank_mask:0xf
	v_fmac_f32_dpp v130, -v149, v114 row_newbcast:0 row_mask:0xf bank_mask:0xf
	v_fmac_f32_dpp v131, -v148, v111 row_newbcast:13 row_mask:0xf bank_mask:0xf
	v_fmac_f32_dpp v132, -v149, v116 row_newbcast:2 row_mask:0xf bank_mask:0xf
	v_fmac_f32_dpp v133, -v149, v117 row_newbcast:3 row_mask:0xf bank_mask:0xf
	v_fmac_f32_dpp v130, -v149, v118 row_newbcast:4 row_mask:0xf bank_mask:0xf
	v_fmac_f32_dpp v131, -v149, v115 row_newbcast:1 row_mask:0xf bank_mask:0xf
	v_fmac_f32_dpp v132, -v149, v120 row_newbcast:6 row_mask:0xf bank_mask:0xf
	v_fmac_f32_dpp v133, -v149, v121 row_newbcast:7 row_mask:0xf bank_mask:0xf
	v_fmac_f32_dpp v130, -v149, v122 row_newbcast:8 row_mask:0xf bank_mask:0xf
	v_fmac_f32_dpp v131, -v149, v119 row_newbcast:5 row_mask:0xf bank_mask:0xf
	v_fmac_f32_dpp v132, -v149, v124 row_newbcast:10 row_mask:0xf bank_mask:0xf
	v_fmac_f32_dpp v133, -v149, v125 row_newbcast:11 row_mask:0xf bank_mask:0xf
	v_fmac_f32_dpp v130, -v149, v126 row_newbcast:12 row_mask:0xf bank_mask:0xf
	v_fmac_f32_dpp v131, -v149, v123 row_newbcast:9 row_mask:0xf bank_mask:0xf
	v_fmac_f32_dpp v132, -v149, v128 row_newbcast:14 row_mask:0xf bank_mask:0xf
	v_fmac_f32_dpp v133, -v149, v129 row_newbcast:15 row_mask:0xf bank_mask:0xf
	v_fmac_f32_dpp v131, -v149, v127 row_newbcast:13 row_mask:0xf bank_mask:0xf
	v_add_f32_e32 v20, v130, v131
	v_add_f32_e32 v21, v132, v133
	v_add_f32_e32 v98, v20, v21
	v_cndmask_b32_e64 v176, -v98, -v99, s[2:3]
	v_cndmask_b32_e64 v177, -v100, -v101, s[2:3]
	v_cndmask_b32_e64 v178, -v102, -v103, s[2:3]
	v_cndmask_b32_e64 v179, -v104, -v105, s[2:3]
	v_cndmask_b32_e64 v180, -v106, -v107, s[2:3]
	v_cndmask_b32_e64 v181, -v108, -v109, s[2:3]
	v_cndmask_b32_e64 v182, -v110, -v111, s[2:3]
	v_cndmask_b32_e64 v183, -v112, -v113, s[2:3]
	v_cndmask_b32_e64 v242, -v114, -v115, s[2:3]
	v_cndmask_b32_e64 v243, -v116, -v117, s[2:3]
	v_cndmask_b32_e64 v244, -v118, -v119, s[2:3]
	v_cndmask_b32_e64 v245, -v120, -v121, s[2:3]
	v_cndmask_b32_e64 v246, -v122, -v123, s[2:3]
	v_cndmask_b32_e64 v247, -v124, -v125, s[2:3]
	v_cndmask_b32_e64 v156, -v126, -v127, s[2:3]
	v_cndmask_b32_e64 v157, -v128, -v129, s[2:3]
	s_waitcnt lgkmcnt(0)
	s_nop 1
	v_mfma_f32_32x32x2_f32 v[2:17], v226, v176, 0
	v_mfma_f32_32x32x2_f32 v[2:17], v227, v177, v[2:17]
	v_mfma_f32_32x32x2_f32 v[2:17], v228, v178, v[2:17]
	v_mfma_f32_32x32x2_f32 v[2:17], v229, v179, v[2:17]
	v_mfma_f32_32x32x2_f32 v[2:17], v230, v180, v[2:17]
	v_mfma_f32_32x32x2_f32 v[2:17], v231, v181, v[2:17]
	v_mfma_f32_32x32x2_f32 v[2:17], v232, v182, v[2:17]
	v_mfma_f32_32x32x2_f32 v[2:17], v233, v183, v[2:17]
	v_mfma_f32_32x32x2_f32 v[2:17], v234, v242, v[2:17]
	v_mfma_f32_32x32x2_f32 v[2:17], v235, v243, v[2:17]
	v_mfma_f32_32x32x2_f32 v[2:17], v236, v244, v[2:17]
	v_mfma_f32_32x32x2_f32 v[2:17], v237, v245, v[2:17]
	v_mfma_f32_32x32x2_f32 v[2:17], v238, v246, v[2:17]
	v_mfma_f32_32x32x2_f32 v[2:17], v239, v247, v[2:17]
	v_mfma_f32_32x32x2_f32 v[2:17], v240, v156, v[2:17]
	v_mfma_f32_32x32x2_f32 v[2:17], v241, v157, v[2:17]
	v_cmp_eq_u32_e32 vcc, 0, v153
	s_nop 1
	v_cndmask_b32_e64 v160, 0, 1.0, vcc
	v_cmp_eq_u32_e32 vcc, 1, v153
	s_nop 1
	v_cndmask_b32_e64 v161, 0, 1.0, vcc
	v_cmp_eq_u32_e32 vcc, 2, v153
	s_nop 1
	v_cndmask_b32_e64 v162, 0, 1.0, vcc
	v_cmp_eq_u32_e32 vcc, 3, v153
	s_nop 1
	v_cndmask_b32_e64 v163, 0, 1.0, vcc
	v_cmp_eq_u32_e32 vcc, 8, v153
	s_nop 1
	v_cndmask_b32_e64 v164, 0, 1.0, vcc
	v_cmp_eq_u32_e32 vcc, 9, v153
	s_nop 1
	v_cndmask_b32_e64 v165, 0, 1.0, vcc
	v_cmp_eq_u32_e32 vcc, 10, v153
	s_nop 1
	v_cndmask_b32_e64 v166, 0, 1.0, vcc
	v_cmp_eq_u32_e32 vcc, 11, v153
	s_nop 1
	v_cndmask_b32_e64 v167, 0, 1.0, vcc
	v_cmp_eq_u32_e32 vcc, 16, v153
	s_nop 1
	v_cndmask_b32_e64 v168, 0, 1.0, vcc
	v_cmp_eq_u32_e32 vcc, 17, v153
	s_nop 1
	v_cndmask_b32_e64 v169, 0, 1.0, vcc
	v_cmp_eq_u32_e32 vcc, 18, v153
	s_nop 1
	v_cndmask_b32_e64 v170, 0, 1.0, vcc
	v_cmp_eq_u32_e32 vcc, 19, v153
	s_nop 1
	v_cndmask_b32_e64 v171, 0, 1.0, vcc
	v_cmp_eq_u32_e32 vcc, 24, v153
	s_nop 1
	v_cndmask_b32_e64 v172, 0, 1.0, vcc
	v_cmp_eq_u32_e32 vcc, 25, v153
	s_nop 1
	v_cndmask_b32_e64 v173, 0, 1.0, vcc
	v_cmp_eq_u32_e32 vcc, 26, v153
	s_nop 1
	v_cndmask_b32_e64 v174, 0, 1.0, vcc
	v_cmp_eq_u32_e32 vcc, 27, v153
	s_nop 1
	v_cndmask_b32_e64 v175, 0, 1.0, vcc
	v_permlane32_swap_b32_e32 v160, v2
	v_permlane32_swap_b32_e32 v161, v3
	v_permlane32_swap_b32_e32 v162, v4
	v_permlane32_swap_b32_e32 v163, v5
	v_permlane32_swap_b32_e32 v164, v6
	v_permlane32_swap_b32_e32 v165, v7
	v_permlane32_swap_b32_e32 v166, v8
	v_permlane32_swap_b32_e32 v167, v9
	v_permlane32_swap_b32_e32 v168, v10
	v_permlane32_swap_b32_e32 v169, v11
	v_permlane32_swap_b32_e32 v170, v12
	v_permlane32_swap_b32_e32 v171, v13
	v_permlane32_swap_b32_e32 v172, v14
	v_permlane32_swap_b32_e32 v173, v15
	v_permlane32_swap_b32_e32 v174, v16
	v_permlane32_swap_b32_e32 v175, v17
	ds_read_b32 v140, v138 offset:6000
	ds_read_b32 v148, v138 offset:5856
	s_waitcnt lgkmcnt(2)
	v_mov_b32_e32 v97, v17
	ds_read_b32 v144, v138 offset:5712
	s_waitcnt lgkmcnt(2)
	v_mul_f32_dpp v133, -v140, v97 row_newbcast:3 row_mask:0xf bank_mask:0xf
	v_add_f32_e32 v96, v16, v133
	ds_read_b32 v140, v138 offset:5568
	s_waitcnt lgkmcnt(2)
	v_mul_f32_dpp v137, -v148, v97 row_newbcast:3 row_mask:0xf bank_mask:0xf
	v_mul_f32_dpp v136, -v148, v96 row_newbcast:2 row_mask:0xf bank_mask:0xf
	v_add_f32_e32 v21, v136, v137
	v_add_f32_e32 v95, v15, v21
	ds_read_b32 v148, v138 offset:5408
	s_waitcnt lgkmcnt(2)
	v_mul_f32_dpp v132, -v144, v96 row_newbcast:2 row_mask:0xf bank_mask:0xf
	v_mul_f32_dpp v133, -v144, v97 row_newbcast:3 row_mask:0xf bank_mask:0xf
	v_mul_f32_dpp v131, -v144, v95 row_newbcast:1 row_mask:0xf bank_mask:0xf
	v_add_f32_e32 v20, v14, v131
	v_add_f32_e32 v21, v132, v133
	v_add_f32_e32 v94, v20, v21
	ds_read_b32 v144, v138 offset:5248
	s_waitcnt lgkmcnt(2)
	v_mul_f32_dpp v135, -v140, v95 row_newbcast:1 row_mask:0xf bank_mask:0xf
	v_mul_f32_dpp v136, -v140, v96 row_newbcast:2 row_mask:0xf bank_mask:0xf
	v_mul_f32_dpp v137, -v140, v97 row_newbcast:3 row_mask:0xf bank_mask:0xf
	v_fmac_f32_dpp v175, -v140, v94 row_newbcast:0 row_mask:0xf bank_mask:0xf
	v_add_f32_e32 v20, v175, v135
	v_add_f32_e32 v21, v136, v137
	v_add_f32_e32 v93, v20, v21
	ds_read_b32 v140, v138 offset:5088
	s_waitcnt lgkmcnt(2)
	v_fmac_f32_dpp v174, -v148, v94 row_newbcast:4 row_mask:0xf bank_mask:0xf
	v_mul_f32_dpp v131, -v148, v95 row_newbcast:5 row_mask:0xf bank_mask:0xf
	v_mul_f32_dpp v132, -v148, v96 row_newbcast:6 row_mask:0xf bank_mask:0xf
	v_mul_f32_dpp v133, -v148, v93 row_newbcast:3 row_mask:0xf bank_mask:0xf
	s_nop 1
	v_fmac_f32_dpp v133, -v148, v97 row_newbcast:7 row_mask:0xf bank_mask:0xf
	v_add_f32_e32 v20, v174, v131
	v_add_f32_e32 v21, v132, v133
	v_add_f32_e32 v92, v20, v21
	ds_read_b32 v148, v138 offset:4928
	s_waitcnt lgkmcnt(2)
	v_mul_f32_dpp v137, -v144, v93 row_newbcast:3 row_mask:0xf bank_mask:0xf
	v_fmac_f32_dpp v173, -v144, v94 row_newbcast:4 row_mask:0xf bank_mask:0xf
	v_mul_f32_dpp v135, -v144, v95 row_newbcast:5 row_mask:0xf bank_mask:0xf
	v_mul_f32_dpp v136, -v144, v92 row_newbcast:2 row_mask:0xf bank_mask:0xf
	v_fmac_f32_dpp v137, -v144, v97 row_newbcast:7 row_mask:0xf bank_mask:0xf
	s_nop 0
	v_fmac_f32_dpp v136, -v144, v96 row_newbcast:6 row_mask:0xf bank_mask:0xf
	v_add_f32_e32 v20, v173, v135
	v_add_f32_e32 v21, v136, v137
	v_add_f32_e32 v91, v20, v21
	ds_read_b32 v144, v138 offset:4752
	s_waitcnt lgkmcnt(2)
	v_mul_f32_dpp v132, -v140, v92 row_newbcast:2 row_mask:0xf bank_mask:0xf
	v_mul_f32_dpp v133, -v140, v93 row_newbcast:3 row_mask:0xf bank_mask:0xf
	v_fmac_f32_dpp v172, -v140, v94 row_newbcast:4 row_mask:0xf bank_mask:0xf
	v_mul_f32_dpp v131, -v140, v91 row_newbcast:1 row_mask:0xf bank_mask:0xf
	v_fmac_f32_dpp v132, -v140, v96 row_newbcast:6 row_mask:0xf bank_mask:0xf
	v_fmac_f32_dpp v133, -v140, v97 row_newbcast:7 row_mask:0xf bank_mask:0xf
	v_fmac_f32_dpp v131, -v140, v95 row_newbcast:5 row_mask:0xf bank_mask:0xf
	v_add_f32_e32 v20, v172, v131
	v_add_f32_e32 v21, v132, v133
	v_add_f32_e32 v90, v20, v21
	ds_read_b32 v140, v138 offset:4576
	s_waitcnt lgkmcnt(2)
	v_mul_f32_dpp v135, -v148, v91 row_newbcast:1 row_mask:0xf bank_mask:0xf
	v_mul_f32_dpp v136, -v148, v92 row_newbcast:2 row_mask:0xf bank_mask:0xf
	v_mul_f32_dpp v137, -v148, v93 row_newbcast:3 row_mask:0xf bank_mask:0xf
	v_fmac_f32_dpp v13, -v148, v90 row_newbcast:0 row_mask:0xf bank_mask:0xf
	v_fmac_f32_dpp v135, -v148, v95 row_newbcast:5 row_mask:0xf bank_mask:0xf
	v_fmac_f32_dpp v136, -v148, v96 row_newbcast:6 row_mask:0xf bank_mask:0xf
	v_fmac_f32_dpp v137, -v148, v97 row_newbcast:7 row_mask:0xf bank_mask:0xf
	v_fmac_f32_dpp v13, -v148, v94 row_newbcast:4 row_mask:0xf bank_mask:0xf
	v_add_f32_e32 v20, v13, v135
	v_add_f32_e32 v21, v136, v137
	v_add_f32_e32 v89, v20, v21
	ds_read_b32 v148, v138 offset:4400
	s_waitcnt lgkmcnt(2)
	v_fmac_f32_dpp v12, -v144, v90 row_newbcast:4 row_mask:0xf bank_mask:0xf
	v_mul_f32_dpp v131, -v144, v91 row_newbcast:5 row_mask:0xf bank_mask:0xf
	v_mul_f32_dpp v132, -v144, v92 row_newbcast:6 row_mask:0xf bank_mask:0xf
	v_mul_f32_dpp v133, -v144, v89 row_newbcast:3 row_mask:0xf bank_mask:0xf
	v_fmac_f32_dpp v12, -v144, v94 row_newbcast:8 row_mask:0xf bank_mask:0xf
	v_fmac_f32_dpp v131, -v144, v95 row_newbcast:9 row_mask:0xf bank_mask:0xf
	v_fmac_f32_dpp v132, -v144, v96 row_newbcast:10 row_mask:0xf bank_mask:0xf
	v_fmac_f32_dpp v133, -v144, v93 row_newbcast:7 row_mask:0xf bank_mask:0xf
	s_nop 1
	v_fmac_f32_dpp v133, -v144, v97 row_newbcast:11 row_mask:0xf bank_mask:0xf
	v_add_f32_e32 v20, v12, v131
	v_add_f32_e32 v21, v132, v133
	v_add_f32_e32 v88, v20, v21
	ds_read_b32 v144, v138 offset:4224
	s_waitcnt lgkmcnt(2)
	v_mul_f32_dpp v137, -v140, v89 row_newbcast:3 row_mask:0xf bank_mask:0xf
	v_fmac_f32_dpp v11, -v140, v90 row_newbcast:4 row_mask:0xf bank_mask:0xf
	v_mul_f32_dpp v135, -v140, v91 row_newbcast:5 row_mask:0xf bank_mask:0xf
	v_mul_f32_dpp v136, -v140, v88 row_newbcast:2 row_mask:0xf bank_mask:0xf
	v_fmac_f32_dpp v137, -v140, v93 row_newbcast:7 row_mask:0xf bank_mask:0xf
	v_fmac_f32_dpp v11, -v140, v94 row_newbcast:8 row_mask:0xf bank_mask:0xf
	v_fmac_f32_dpp v135, -v140, v95 row_newbcast:9 row_mask:0xf bank_mask:0xf
	v_fmac_f32_dpp v136, -v140, v92 row_newbcast:6 row_mask:0xf bank_mask:0xf
	v_fmac_f32_dpp v137, -v140, v97 row_newbcast:11 row_mask:0xf bank_mask:0xf
	s_nop 0
	v_fmac_f32_dpp v136, -v140, v96 row_newbcast:10 row_mask:0xf bank_mask:0xf
	v_add_f32_e32 v20, v11, v135
	v_add_f32_e32 v21, v136, v137
	v_add_f32_e32 v87, v20, v21
	ds_read_b32 v140, v138 offset:4032
	s_waitcnt lgkmcnt(2)
	v_mul_f32_dpp v132, -v148, v88 row_newbcast:2 row_mask:0xf bank_mask:0xf
	v_mul_f32_dpp v133, -v148, v89 row_newbcast:3 row_mask:0xf bank_mask:0xf
	v_fmac_f32_dpp v10, -v148, v90 row_newbcast:4 row_mask:0xf bank_mask:0xf
	v_mul_f32_dpp v131, -v148, v87 row_newbcast:1 row_mask:0xf bank_mask:0xf
	v_fmac_f32_dpp v132, -v148, v92 row_newbcast:6 row_mask:0xf bank_mask:0xf
	v_fmac_f32_dpp v133, -v148, v93 row_newbcast:7 row_mask:0xf bank_mask:0xf
	v_fmac_f32_dpp v10, -v148, v94 row_newbcast:8 row_mask:0xf bank_mask:0xf
	v_fmac_f32_dpp v131, -v148, v91 row_newbcast:5 row_mask:0xf bank_mask:0xf
	v_fmac_f32_dpp v132, -v148, v96 row_newbcast:10 row_mask:0xf bank_mask:0xf
	v_fmac_f32_dpp v133, -v148, v97 row_newbcast:11 row_mask:0xf bank_mask:0xf
	v_fmac_f32_dpp v131, -v148, v95 row_newbcast:9 row_mask:0xf bank_mask:0xf
	v_add_f32_e32 v20, v10, v131
	v_add_f32_e32 v21, v132, v133
	v_add_f32_e32 v86, v20, v21
	ds_read_b32 v148, v138 offset:3840
	s_waitcnt lgkmcnt(2)
	v_mul_f32_dpp v135, -v144, v87 row_newbcast:1 row_mask:0xf bank_mask:0xf
	v_mul_f32_dpp v136, -v144, v88 row_newbcast:2 row_mask:0xf bank_mask:0xf
	v_mul_f32_dpp v137, -v144, v89 row_newbcast:3 row_mask:0xf bank_mask:0xf
	v_fmac_f32_dpp v171, -v144, v86 row_newbcast:0 row_mask:0xf bank_mask:0xf
	v_fmac_f32_dpp v135, -v144, v91 row_newbcast:5 row_mask:0xf bank_mask:0xf
	v_fmac_f32_dpp v136, -v144, v92 row_newbcast:6 row_mask:0xf bank_mask:0xf
	v_fmac_f32_dpp v137, -v144, v93 row_newbcast:7 row_mask:0xf bank_mask:0xf
	v_fmac_f32_dpp v171, -v144, v90 row_newbcast:4 row_mask:0xf bank_mask:0xf
	v_fmac_f32_dpp v135, -v144, v95 row_newbcast:9 row_mask:0xf bank_mask:0xf
	v_fmac_f32_dpp v136, -v144, v96 row_newbcast:10 row_mask:0xf bank_mask:0xf
	v_fmac_f32_dpp v137, -v144, v97 row_newbcast:11 row_mask:0xf bank_mask:0xf
	v_fmac_f32_dpp v171, -v144, v94 row_newbcast:8 row_mask:0xf bank_mask:0xf
	v_add_f32_e32 v20, v171, v135
	v_add_f32_e32 v21, v136, v137
	v_add_f32_e32 v85, v20, v21
	ds_read_b32 v144, v138 offset:3648
	s_waitcnt lgkmcnt(2)
	v_fmac_f32_dpp v170, -v140, v86 row_newbcast:4 row_mask:0xf bank_mask:0xf
	v_mul_f32_dpp v131, -v140, v87 row_newbcast:5 row_mask:0xf bank_mask:0xf
	v_mul_f32_dpp v132, -v140, v88 row_newbcast:6 row_mask:0xf bank_mask:0xf
	v_mul_f32_dpp v133, -v140, v85 row_newbcast:3 row_mask:0xf bank_mask:0xf
	v_fmac_f32_dpp v170, -v140, v90 row_newbcast:8 row_mask:0xf bank_mask:0xf
	v_fmac_f32_dpp v131, -v140, v91 row_newbcast:9 row_mask:0xf bank_mask:0xf
	v_fmac_f32_dpp v132, -v140, v92 row_newbcast:10 row_mask:0xf bank_mask:0xf
	v_fmac_f32_dpp v133, -v140, v89 row_newbcast:7 row_mask:0xf bank_mask:0xf
	v_fmac_f32_dpp v170, -v140, v94 row_newbcast:12 row_mask:0xf bank_mask:0xf
	v_fmac_f32_dpp v131, -v140, v95 row_newbcast:13 row_mask:0xf bank_mask:0xf
	v_fmac_f32_dpp v132, -v140, v96 row_newbcast:14 row_mask:0xf bank_mask:0xf
	v_fmac_f32_dpp v133, -v140, v93 row_newbcast:11 row_mask:0xf bank_mask:0xf
	s_nop 1
	v_fmac_f32_dpp v133, -v140, v97 row_newbcast:15 row_mask:0xf bank_mask:0xf
	v_add_f32_e32 v20, v170, v131
	v_add_f32_e32 v21, v132, v133
	v_add_f32_e32 v84, v20, v21
	ds_read_b32 v140, v138 offset:3456
	s_waitcnt lgkmcnt(2)
	v_mul_f32_dpp v137, -v148, v85 row_newbcast:3 row_mask:0xf bank_mask:0xf
	v_fmac_f32_dpp v169, -v148, v86 row_newbcast:4 row_mask:0xf bank_mask:0xf
	v_mul_f32_dpp v135, -v148, v87 row_newbcast:5 row_mask:0xf bank_mask:0xf
	v_mul_f32_dpp v136, -v148, v84 row_newbcast:2 row_mask:0xf bank_mask:0xf
	v_fmac_f32_dpp v137, -v148, v89 row_newbcast:7 row_mask:0xf bank_mask:0xf
	v_fmac_f32_dpp v169, -v148, v90 row_newbcast:8 row_mask:0xf bank_mask:0xf
	v_fmac_f32_dpp v135, -v148, v91 row_newbcast:9 row_mask:0xf bank_mask:0xf
	v_fmac_f32_dpp v136, -v148, v88 row_newbcast:6 row_mask:0xf bank_mask:0xf
	v_fmac_f32_dpp v137, -v148, v93 row_newbcast:11 row_mask:0xf bank_mask:0xf
	v_fmac_f32_dpp v169, -v148, v94 row_newbcast:12 row_mask:0xf bank_mask:0xf
	v_fmac_f32_dpp v135, -v148, v95 row_newbcast:13 row_mask:0xf bank_mask:0xf
	v_fmac_f32_dpp v136, -v148, v92 row_newbcast:10 row_mask:0xf bank_mask:0xf
	v_fmac_f32_dpp v137, -v148, v97 row_newbcast:15 row_mask:0xf bank_mask:0xf
	s_nop 0
	v_fmac_f32_dpp v136, -v148, v96 row_newbcast:14 row_mask:0xf bank_mask:0xf
	v_add_f32_e32 v20, v169, v135
	v_add_f32_e32 v21, v136, v137
	v_add_f32_e32 v83, v20, v21
	ds_read_b32 v148, v138 offset:3248
	ds_read_b32 v149, v138 offset:3312
	s_waitcnt lgkmcnt(3)
	v_mul_f32_dpp v132, -v144, v84 row_newbcast:2 row_mask:0xf bank_mask:0xf
	v_mul_f32_dpp v133, -v144, v85 row_newbcast:3 row_mask:0xf bank_mask:0xf
	v_fmac_f32_dpp v168, -v144, v86 row_newbcast:4 row_mask:0xf bank_mask:0xf
	v_mul_f32_dpp v131, -v144, v83 row_newbcast:1 row_mask:0xf bank_mask:0xf
	v_fmac_f32_dpp v132, -v144, v88 row_newbcast:6 row_mask:0xf bank_mask:0xf
	v_fmac_f32_dpp v133, -v144, v89 row_newbcast:7 row_mask:0xf bank_mask:0xf
	v_fmac_f32_dpp v168, -v144, v90 row_newbcast:8 row_mask:0xf bank_mask:0xf
	v_fmac_f32_dpp v131, -v144, v87 row_newbcast:5 row_mask:0xf bank_mask:0xf
	v_fmac_f32_dpp v132, -v144, v92 row_newbcast:10 row_mask:0xf bank_mask:0xf
	v_fmac_f32_dpp v133, -v144, v93 row_newbcast:11 row_mask:0xf bank_mask:0xf
	v_fmac_f32_dpp v168, -v144, v94 row_newbcast:12 row_mask:0xf bank_mask:0xf
	v_fmac_f32_dpp v131, -v144, v91 row_newbcast:9 row_mask:0xf bank_mask:0xf
	v_fmac_f32_dpp v132, -v144, v96 row_newbcast:14 row_mask:0xf bank_mask:0xf
	v_fmac_f32_dpp v133, -v144, v97 row_newbcast:15 row_mask:0xf bank_mask:0xf
	v_fmac_f32_dpp v131, -v144, v95 row_newbcast:13 row_mask:0xf bank_mask:0xf
	v_add_f32_e32 v20, v168, v131
	v_add_f32_e32 v21, v132, v133
	v_add_f32_e32 v82, v20, v21
	ds_read_b32 v144, v138 offset:3040
	ds_read_b32 v145, v138 offset:3104
	s_waitcnt lgkmcnt(4)
	v_mul_f32_dpp v135, -v140, v83 row_newbcast:1 row_mask:0xf bank_mask:0xf
	v_mul_f32_dpp v136, -v140, v84 row_newbcast:2 row_mask:0xf bank_mask:0xf
	v_mul_f32_dpp v137, -v140, v85 row_newbcast:3 row_mask:0xf bank_mask:0xf
	v_fmac_f32_dpp v9, -v140, v82 row_newbcast:0 row_mask:0xf bank_mask:0xf
	v_fmac_f32_dpp v135, -v140, v87 row_newbcast:5 row_mask:0xf bank_mask:0xf
	v_fmac_f32_dpp v136, -v140, v88 row_newbcast:6 row_mask:0xf bank_mask:0xf
	v_fmac_f32_dpp v137, -v140, v89 row_newbcast:7 row_mask:0xf bank_mask:0xf
	v_fmac_f32_dpp v9, -v140, v86 row_newbcast:4 row_mask:0xf bank_mask:0xf
	v_fmac_f32_dpp v135, -v140, v91 row_newbcast:9 row_mask:0xf bank_mask:0xf
	v_fmac_f32_dpp v136, -v140, v92 row_newbcast:10 row_mask:0xf bank_mask:0xf
	v_fmac_f32_dpp v137, -v140, v93 row_newbcast:11 row_mask:0xf bank_mask:0xf
	v_fmac_f32_dpp v9, -v140, v90 row_newbcast:8 row_mask:0xf bank_mask:0xf
	v_fmac_f32_dpp v135, -v140, v95 row_newbcast:13 row_mask:0xf bank_mask:0xf
	v_fmac_f32_dpp v136, -v140, v96 row_newbcast:14 row_mask:0xf bank_mask:0xf
	v_fmac_f32_dpp v137, -v140, v97 row_newbcast:15 row_mask:0xf bank_mask:0xf
	v_fmac_f32_dpp v9, -v140, v94 row_newbcast:12 row_mask:0xf bank_mask:0xf
	v_add_f32_e32 v20, v9, v135
	v_add_f32_e32 v21, v136, v137
	v_add_f32_e32 v81, v20, v21
	ds_read_b32 v140, v138 offset:2832
	ds_read_b32 v141, v138 offset:2896
	s_waitcnt lgkmcnt(4)
	v_fmac_f32_dpp v8, -v148, v82 row_newbcast:4 row_mask:0xf bank_mask:0xf
	v_mul_f32_dpp v131, -v148, v83 row_newbcast:5 row_mask:0xf bank_mask:0xf
	v_mul_f32_dpp v132, -v148, v84 row_newbcast:6 row_mask:0xf bank_mask:0xf
	v_mul_f32_dpp v133, -v148, v81 row_newbcast:3 row_mask:0xf bank_mask:0xf
	v_fmac_f32_dpp v8, -v148, v86 row_newbcast:8 row_mask:0xf bank_mask:0xf
	v_fmac_f32_dpp v131, -v148, v87 row_newbcast:9 row_mask:0xf bank_mask:0xf
	v_fmac_f32_dpp v132, -v148, v88 row_newbcast:10 row_mask:0xf bank_mask:0xf
	v_fmac_f32_dpp v133, -v148, v85 row_newbcast:7 row_mask:0xf bank_mask:0xf
	v_fmac_f32_dpp v8, -v148, v90 row_newbcast:12 row_mask:0xf bank_mask:0xf
	v_fmac_f32_dpp v131, -v148, v91 row_newbcast:13 row_mask:0xf bank_mask:0xf
	v_fmac_f32_dpp v132, -v148, v92 row_newbcast:14 row_mask:0xf bank_mask:0xf
	v_fmac_f32_dpp v133, -v148, v89 row_newbcast:11 row_mask:0xf bank_mask:0xf
	v_fmac_f32_dpp v8, -v149, v94 row_newbcast:0 row_mask:0xf bank_mask:0xf
	v_fmac_f32_dpp v131, -v149, v95 row_newbcast:1 row_mask:0xf bank_mask:0xf
	v_fmac_f32_dpp v132, -v149, v96 row_newbcast:2 row_mask:0xf bank_mask:0xf
	v_fmac_f32_dpp v133, -v148, v93 row_newbcast:15 row_mask:0xf bank_mask:0xf
	s_nop 1
	v_fmac_f32_dpp v133, -v149, v97 row_newbcast:3 row_mask:0xf bank_mask:0xf
	v_add_f32_e32 v20, v8, v131
	v_add_f32_e32 v21, v132, v133
	v_add_f32_e32 v80, v20, v21
	ds_read_b32 v148, v138 offset:2624
	ds_read_b32 v149, v138 offset:2688
	s_waitcnt lgkmcnt(4)
	v_mul_f32_dpp v137, -v144, v81 row_newbcast:3 row_mask:0xf bank_mask:0xf
	v_fmac_f32_dpp v7, -v144, v82 row_newbcast:4 row_mask:0xf bank_mask:0xf
	v_mul_f32_dpp v135, -v144, v83 row_newbcast:5 row_mask:0xf bank_mask:0xf
	v_mul_f32_dpp v136, -v144, v80 row_newbcast:2 row_mask:0xf bank_mask:0xf
	v_fmac_f32_dpp v137, -v144, v85 row_newbcast:7 row_mask:0xf bank_mask:0xf
	v_fmac_f32_dpp v7, -v144, v86 row_newbcast:8 row_mask:0xf bank_mask:0xf
	v_fmac_f32_dpp v135, -v144, v87 row_newbcast:9 row_mask:0xf bank_mask:0xf
	v_fmac_f32_dpp v136, -v144, v84 row_newbcast:6 row_mask:0xf bank_mask:0xf
	v_fmac_f32_dpp v137, -v144, v89 row_newbcast:11 row_mask:0xf bank_mask:0xf
	v_fmac_f32_dpp v7, -v144, v90 row_newbcast:12 row_mask:0xf bank_mask:0xf
	v_fmac_f32_dpp v135, -v144, v91 row_newbcast:13 row_mask:0xf bank_mask:0xf
	v_fmac_f32_dpp v136, -v144, v88 row_newbcast:10 row_mask:0xf bank_mask:0xf
	v_fmac_f32_dpp v137, -v144, v93 row_newbcast:15 row_mask:0xf bank_mask:0xf
	v_fmac_f32_dpp v7, -v145, v94 row_newbcast:0 row_mask:0xf bank_mask:0xf
	v_fmac_f32_dpp v135, -v145, v95 row_newbcast:1 row_mask:0xf bank_mask:0xf
	v_fmac_f32_dpp v136, -v144, v92 row_newbcast:14 row_mask:0xf bank_mask:0xf
	v_fmac_f32_dpp v137, -v145, v97 row_newbcast:3 row_mask:0xf bank_mask:0xf
	s_nop 0
	v_fmac_f32_dpp v136, -v145, v96 row_newbcast:2 row_mask:0xf bank_mask:0xf
	v_add_f32_e32 v20, v7, v135
	v_add_f32_e32 v21, v136, v137
	v_add_f32_e32 v79, v20, v21
	ds_read_b32 v144, v138 offset:2400
	ds_read_b32 v145, v138 offset:2464
	s_waitcnt lgkmcnt(4)
	v_mul_f32_dpp v132, -v140, v80 row_newbcast:2 row_mask:0xf bank_mask:0xf
	v_mul_f32_dpp v133, -v140, v81 row_newbcast:3 row_mask:0xf bank_mask:0xf
	v_fmac_f32_dpp v6, -v140, v82 row_newbcast:4 row_mask:0xf bank_mask:0xf
	v_mul_f32_dpp v131, -v140, v79 row_newbcast:1 row_mask:0xf bank_mask:0xf
	v_fmac_f32_dpp v132, -v140, v84 row_newbcast:6 row_mask:0xf bank_mask:0xf
	v_fmac_f32_dpp v133, -v140, v85 row_newbcast:7 row_mask:0xf bank_mask:0xf
	v_fmac_f32_dpp v6, -v140, v86 row_newbcast:8 row_mask:0xf bank_mask:0xf
	v_fmac_f32_dpp v131, -v140, v83 row_newbcast:5 row_mask:0xf bank_mask:0xf
	v_fmac_f32_dpp v132, -v140, v88 row_newbcast:10 row_mask:0xf bank_mask:0xf
	v_fmac_f32_dpp v133, -v140, v89 row_newbcast:11 row_mask:0xf bank_mask:0xf
	v_fmac_f32_dpp v6, -v140, v90 row_newbcast:12 row_mask:0xf bank_mask:0xf
	v_fmac_f32_dpp v131, -v140, v87 row_newbcast:9 row_mask:0xf bank_mask:0xf
	v_fmac_f32_dpp v132, -v140, v92 row_newbcast:14 row_mask:0xf bank_mask:0xf
	v_fmac_f32_dpp v133, -v140, v93 row_newbcast:15 row_mask:0xf bank_mask:0xf
	v_fmac_f32_dpp v6, -v141, v94 row_newbcast:0 row_mask:0xf bank_mask:0xf
	v_fmac_f32_dpp v131, -v140, v91 row_newbcast:13 row_mask:0xf bank_mask:0xf
	v_fmac_f32_dpp v132, -v141, v96 row_newbcast:2 row_mask:0xf bank_mask:0xf
	v_fmac_f32_dpp v133, -v141, v97 row_newbcast:3 row_mask:0xf bank_mask:0xf
	v_fmac_f32_dpp v131, -v141, v95 row_newbcast:1 row_mask:0xf bank_mask:0xf
	v_add_f32_e32 v20, v6, v131
	v_add_f32_e32 v21, v132, v133
	v_add_f32_e32 v78, v20, v21
	ds_read_b32 v140, v138 offset:2176
	ds_read_b32 v141, v138 offset:2240
	s_waitcnt lgkmcnt(4)
	v_mul_f32_dpp v135, -v148, v79 row_newbcast:1 row_mask:0xf bank_mask:0xf
	v_mul_f32_dpp v136, -v148, v80 row_newbcast:2 row_mask:0xf bank_mask:0xf
	v_mul_f32_dpp v137, -v148, v81 row_newbcast:3 row_mask:0xf bank_mask:0xf
	v_fmac_f32_dpp v167, -v148, v78 row_newbcast:0 row_mask:0xf bank_mask:0xf
	v_fmac_f32_dpp v135, -v148, v83 row_newbcast:5 row_mask:0xf bank_mask:0xf
	v_fmac_f32_dpp v136, -v148, v84 row_newbcast:6 row_mask:0xf bank_mask:0xf
	v_fmac_f32_dpp v137, -v148, v85 row_newbcast:7 row_mask:0xf bank_mask:0xf
	v_fmac_f32_dpp v167, -v148, v82 row_newbcast:4 row_mask:0xf bank_mask:0xf
	v_fmac_f32_dpp v135, -v148, v87 row_newbcast:9 row_mask:0xf bank_mask:0xf
	v_fmac_f32_dpp v136, -v148, v88 row_newbcast:10 row_mask:0xf bank_mask:0xf
	v_fmac_f32_dpp v137, -v148, v89 row_newbcast:11 row_mask:0xf bank_mask:0xf
	v_fmac_f32_dpp v167, -v148, v86 row_newbcast:8 row_mask:0xf bank_mask:0xf
	v_fmac_f32_dpp v135, -v148, v91 row_newbcast:13 row_mask:0xf bank_mask:0xf
	v_fmac_f32_dpp v136, -v148, v92 row_newbcast:14 row_mask:0xf bank_mask:0xf
	v_fmac_f32_dpp v137, -v148, v93 row_newbcast:15 row_mask:0xf bank_mask:0xf
	v_fmac_f32_dpp v167, -v148, v90 row_newbcast:12 row_mask:0xf bank_mask:0xf
	v_fmac_f32_dpp v135, -v149, v95 row_newbcast:1 row_mask:0xf bank_mask:0xf
	v_fmac_f32_dpp v136, -v149, v96 row_newbcast:2 row_mask:0xf bank_mask:0xf
	v_fmac_f32_dpp v137, -v149, v97 row_newbcast:3 row_mask:0xf bank_mask:0xf
	v_fmac_f32_dpp v167, -v149, v94 row_newbcast:0 row_mask:0xf bank_mask:0xf
	v_add_f32_e32 v20, v167, v135
	v_add_f32_e32 v21, v136, v137
	v_add_f32_e32 v77, v20, v21
	ds_read_b32 v148, v138 offset:1952
	ds_read_b32 v149, v138 offset:2016
	s_waitcnt lgkmcnt(4)
	v_fmac_f32_dpp v166, -v144, v78 row_newbcast:4 row_mask:0xf bank_mask:0xf
	v_mul_f32_dpp v131, -v144, v79 row_newbcast:5 row_mask:0xf bank_mask:0xf
	v_mul_f32_dpp v132, -v144, v80 row_newbcast:6 row_mask:0xf bank_mask:0xf
	v_mul_f32_dpp v133, -v144, v77 row_newbcast:3 row_mask:0xf bank_mask:0xf
	v_fmac_f32_dpp v166, -v144, v82 row_newbcast:8 row_mask:0xf bank_mask:0xf
	v_fmac_f32_dpp v131, -v144, v83 row_newbcast:9 row_mask:0xf bank_mask:0xf
	v_fmac_f32_dpp v132, -v144, v84 row_newbcast:10 row_mask:0xf bank_mask:0xf
	v_fmac_f32_dpp v133, -v144, v81 row_newbcast:7 row_mask:0xf bank_mask:0xf
	v_fmac_f32_dpp v166, -v144, v86 row_newbcast:12 row_mask:0xf bank_mask:0xf
	v_fmac_f32_dpp v131, -v144, v87 row_newbcast:13 row_mask:0xf bank_mask:0xf
	v_fmac_f32_dpp v132, -v144, v88 row_newbcast:14 row_mask:0xf bank_mask:0xf
	v_fmac_f32_dpp v133, -v144, v85 row_newbcast:11 row_mask:0xf bank_mask:0xf
	v_fmac_f32_dpp v166, -v145, v90 row_newbcast:0 row_mask:0xf bank_mask:0xf
	v_fmac_f32_dpp v131, -v145, v91 row_newbcast:1 row_mask:0xf bank_mask:0xf
	v_fmac_f32_dpp v132, -v145, v92 row_newbcast:2 row_mask:0xf bank_mask:0xf
	v_fmac_f32_dpp v133, -v144, v89 row_newbcast:15 row_mask:0xf bank_mask:0xf
	v_fmac_f32_dpp v166, -v145, v94 row_newbcast:4 row_mask:0xf bank_mask:0xf
	v_fmac_f32_dpp v131, -v145, v95 row_newbcast:5 row_mask:0xf bank_mask:0xf
	v_fmac_f32_dpp v132, -v145, v96 row_newbcast:6 row_mask:0xf bank_mask:0xf
	v_fmac_f32_dpp v133, -v145, v93 row_newbcast:3 row_mask:0xf bank_mask:0xf
	s_nop 1
	v_fmac_f32_dpp v133, -v145, v97 row_newbcast:7 row_mask:0xf bank_mask:0xf
	v_add_f32_e32 v20, v166, v131
	v_add_f32_e32 v21, v132, v133
	v_add_f32_e32 v76, v20, v21
	ds_read_b32 v144, v138 offset:1728
	ds_read_b32 v145, v138 offset:1792
	s_waitcnt lgkmcnt(4)
	v_mul_f32_dpp v137, -v140, v77 row_newbcast:3 row_mask:0xf bank_mask:0xf
	v_fmac_f32_dpp v165, -v140, v78 row_newbcast:4 row_mask:0xf bank_mask:0xf
	v_mul_f32_dpp v135, -v140, v79 row_newbcast:5 row_mask:0xf bank_mask:0xf
	v_mul_f32_dpp v136, -v140, v76 row_newbcast:2 row_mask:0xf bank_mask:0xf
	v_fmac_f32_dpp v137, -v140, v81 row_newbcast:7 row_mask:0xf bank_mask:0xf
	v_fmac_f32_dpp v165, -v140, v82 row_newbcast:8 row_mask:0xf bank_mask:0xf
	v_fmac_f32_dpp v135, -v140, v83 row_newbcast:9 row_mask:0xf bank_mask:0xf
	v_fmac_f32_dpp v136, -v140, v80 row_newbcast:6 row_mask:0xf bank_mask:0xf
	v_fmac_f32_dpp v137, -v140, v85 row_newbcast:11 row_mask:0xf bank_mask:0xf
	v_fmac_f32_dpp v165, -v140, v86 row_newbcast:12 row_mask:0xf bank_mask:0xf
	v_fmac_f32_dpp v135, -v140, v87 row_newbcast:13 row_mask:0xf bank_mask:0xf
	v_fmac_f32_dpp v136, -v140, v84 row_newbcast:10 row_mask:0xf bank_mask:0xf
	v_fmac_f32_dpp v137, -v140, v89 row_newbcast:15 row_mask:0xf bank_mask:0xf
	v_fmac_f32_dpp v165, -v141, v90 row_newbcast:0 row_mask:0xf bank_mask:0xf
	v_fmac_f32_dpp v135, -v141, v91 row_newbcast:1 row_mask:0xf bank_mask:0xf
	v_fmac_f32_dpp v136, -v140, v88 row_newbcast:14 row_mask:0xf bank_mask:0xf
	v_fmac_f32_dpp v137, -v141, v93 row_newbcast:3 row_mask:0xf bank_mask:0xf
	v_fmac_f32_dpp v165, -v141, v94 row_newbcast:4 row_mask:0xf bank_mask:0xf
	v_fmac_f32_dpp v135, -v141, v95 row_newbcast:5 row_mask:0xf bank_mask:0xf
	v_fmac_f32_dpp v136, -v141, v92 row_newbcast:2 row_mask:0xf bank_mask:0xf
	v_fmac_f32_dpp v137, -v141, v97 row_newbcast:7 row_mask:0xf bank_mask:0xf
	s_nop 0
	v_fmac_f32_dpp v136, -v141, v96 row_newbcast:6 row_mask:0xf bank_mask:0xf
	v_add_f32_e32 v20, v165, v135
	v_add_f32_e32 v21, v136, v137
	v_add_f32_e32 v75, v20, v21
	ds_read_b32 v140, v138 offset:1488
	ds_read_b32 v141, v138 offset:1552
	s_waitcnt lgkmcnt(4)
	v_mul_f32_dpp v132, -v148, v76 row_newbcast:2 row_mask:0xf bank_mask:0xf
	v_mul_f32_dpp v133, -v148, v77 row_newbcast:3 row_mask:0xf bank_mask:0xf
	v_fmac_f32_dpp v164, -v148, v78 row_newbcast:4 row_mask:0xf bank_mask:0xf
	v_mul_f32_dpp v131, -v148, v75 row_newbcast:1 row_mask:0xf bank_mask:0xf
	v_fmac_f32_dpp v132, -v148, v80 row_newbcast:6 row_mask:0xf bank_mask:0xf
	v_fmac_f32_dpp v133, -v148, v81 row_newbcast:7 row_mask:0xf bank_mask:0xf
	v_fmac_f32_dpp v164, -v148, v82 row_newbcast:8 row_mask:0xf bank_mask:0xf
	v_fmac_f32_dpp v131, -v148, v79 row_newbcast:5 row_mask:0xf bank_mask:0xf
	v_fmac_f32_dpp v132, -v148, v84 row_newbcast:10 row_mask:0xf bank_mask:0xf
	v_fmac_f32_dpp v133, -v148, v85 row_newbcast:11 row_mask:0xf bank_mask:0xf
	v_fmac_f32_dpp v164, -v148, v86 row_newbcast:12 row_mask:0xf bank_mask:0xf
	v_fmac_f32_dpp v131, -v148, v83 row_newbcast:9 row_mask:0xf bank_mask:0xf
	v_fmac_f32_dpp v132, -v148, v88 row_newbcast:14 row_mask:0xf bank_mask:0xf
	v_fmac_f32_dpp v133, -v148, v89 row_newbcast:15 row_mask:0xf bank_mask:0xf
	v_fmac_f32_dpp v164, -v149, v90 row_newbcast:0 row_mask:0xf bank_mask:0xf
	v_fmac_f32_dpp v131, -v148, v87 row_newbcast:13 row_mask:0xf bank_mask:0xf
	v_fmac_f32_dpp v132, -v149, v92 row_newbcast:2 row_mask:0xf bank_mask:0xf
	v_fmac_f32_dpp v133, -v149, v93 row_newbcast:3 row_mask:0xf bank_mask:0xf
	v_fmac_f32_dpp v164, -v149, v94 row_newbcast:4 row_mask:0xf bank_mask:0xf
	v_fmac_f32_dpp v131, -v149, v91 row_newbcast:1 row_mask:0xf bank_mask:0xf
	v_fmac_f32_dpp v132, -v149, v96 row_newbcast:6 row_mask:0xf bank_mask:0xf
	v_fmac_f32_dpp v133, -v149, v97 row_newbcast:7 row_mask:0xf bank_mask:0xf
	v_fmac_f32_dpp v131, -v149, v95 row_newbcast:5 row_mask:0xf bank_mask:0xf
	v_add_f32_e32 v20, v164, v131
	v_add_f32_e32 v21, v132, v133
	v_add_f32_e32 v74, v20, v21
	ds_read_b32 v148, v138 offset:1248
	ds_read_b32 v149, v138 offset:1312
	s_waitcnt lgkmcnt(4)
	v_mul_f32_dpp v135, -v144, v75 row_newbcast:1 row_mask:0xf bank_mask:0xf
	v_mul_f32_dpp v136, -v144, v76 row_newbcast:2 row_mask:0xf bank_mask:0xf
	v_mul_f32_dpp v137, -v144, v77 row_newbcast:3 row_mask:0xf bank_mask:0xf
	v_fmac_f32_dpp v5, -v144, v74 row_newbcast:0 row_mask:0xf bank_mask:0xf
	v_fmac_f32_dpp v135, -v144, v79 row_newbcast:5 row_mask:0xf bank_mask:0xf
	v_fmac_f32_dpp v136, -v144, v80 row_newbcast:6 row_mask:0xf bank_mask:0xf
	v_fmac_f32_dpp v137, -v144, v81 row_newbcast:7 row_mask:0xf bank_mask:0xf
	v_fmac_f32_dpp v5, -v144, v78 row_newbcast:4 row_mask:0xf bank_mask:0xf
	v_fmac_f32_dpp v135, -v144, v83 row_newbcast:9 row_mask:0xf bank_mask:0xf
	v_fmac_f32_dpp v136, -v144, v84 row_newbcast:10 row_mask:0xf bank_mask:0xf
	v_fmac_f32_dpp v137, -v144, v85 row_newbcast:11 row_mask:0xf bank_mask:0xf
	v_fmac_f32_dpp v5, -v144, v82 row_newbcast:8 row_mask:0xf bank_mask:0xf
	v_fmac_f32_dpp v135, -v144, v87 row_newbcast:13 row_mask:0xf bank_mask:0xf
	v_fmac_f32_dpp v136, -v144, v88 row_newbcast:14 row_mask:0xf bank_mask:0xf
	v_fmac_f32_dpp v137, -v144, v89 row_newbcast:15 row_mask:0xf bank_mask:0xf
	v_fmac_f32_dpp v5, -v144, v86 row_newbcast:12 row_mask:0xf bank_mask:0xf
	v_fmac_f32_dpp v135, -v145, v91 row_newbcast:1 row_mask:0xf bank_mask:0xf
	v_fmac_f32_dpp v136, -v145, v92 row_newbcast:2 row_mask:0xf bank_mask:0xf
	v_fmac_f32_dpp v137, -v145, v93 row_newbcast:3 row_mask:0xf bank_mask:0xf
	v_fmac_f32_dpp v5, -v145, v90 row_newbcast:0 row_mask:0xf bank_mask:0xf
	v_fmac_f32_dpp v135, -v145, v95 row_newbcast:5 row_mask:0xf bank_mask:0xf
	v_fmac_f32_dpp v136, -v145, v96 row_newbcast:6 row_mask:0xf bank_mask:0xf
	v_fmac_f32_dpp v137, -v145, v97 row_newbcast:7 row_mask:0xf bank_mask:0xf
	v_fmac_f32_dpp v5, -v145, v94 row_newbcast:4 row_mask:0xf bank_mask:0xf
	v_add_f32_e32 v20, v5, v135
	v_add_f32_e32 v21, v136, v137
	v_add_f32_e32 v73, v20, v21
	ds_read_b32 v144, v138 offset:1008
	ds_read_b32 v145, v138 offset:1072
	s_waitcnt lgkmcnt(4)
	v_fmac_f32_dpp v4, -v140, v74 row_newbcast:4 row_mask:0xf bank_mask:0xf
	v_mul_f32_dpp v131, -v140, v75 row_newbcast:5 row_mask:0xf bank_mask:0xf
	v_mul_f32_dpp v132, -v140, v76 row_newbcast:6 row_mask:0xf bank_mask:0xf
	v_mul_f32_dpp v133, -v140, v73 row_newbcast:3 row_mask:0xf bank_mask:0xf
	v_fmac_f32_dpp v4, -v140, v78 row_newbcast:8 row_mask:0xf bank_mask:0xf
	v_fmac_f32_dpp v131, -v140, v79 row_newbcast:9 row_mask:0xf bank_mask:0xf
	v_fmac_f32_dpp v132, -v140, v80 row_newbcast:10 row_mask:0xf bank_mask:0xf
	v_fmac_f32_dpp v133, -v140, v77 row_newbcast:7 row_mask:0xf bank_mask:0xf
	v_fmac_f32_dpp v4, -v140, v82 row_newbcast:12 row_mask:0xf bank_mask:0xf
	v_fmac_f32_dpp v131, -v140, v83 row_newbcast:13 row_mask:0xf bank_mask:0xf
	v_fmac_f32_dpp v132, -v140, v84 row_newbcast:14 row_mask:0xf bank_mask:0xf
	v_fmac_f32_dpp v133, -v140, v81 row_newbcast:11 row_mask:0xf bank_mask:0xf
	v_fmac_f32_dpp v4, -v141, v86 row_newbcast:0 row_mask:0xf bank_mask:0xf
	v_fmac_f32_dpp v131, -v141, v87 row_newbcast:1 row_mask:0xf bank_mask:0xf
	v_fmac_f32_dpp v132, -v141, v88 row_newbcast:2 row_mask:0xf bank_mask:0xf
	v_fmac_f32_dpp v133, -v140, v85 row_newbcast:15 row_mask:0xf bank_mask:0xf
	v_fmac_f32_dpp v4, -v141, v90 row_newbcast:4 row_mask:0xf bank_mask:0xf
	v_fmac_f32_dpp v131, -v141, v91 row_newbcast:5 row_mask:0xf bank_mask:0xf
	v_fmac_f32_dpp v132, -v141, v92 row_newbcast:6 row_mask:0xf bank_mask:0xf
	v_fmac_f32_dpp v133, -v141, v89 row_newbcast:3 row_mask:0xf bank_mask:0xf
	v_fmac_f32_dpp v4, -v141, v94 row_newbcast:8 row_mask:0xf bank_mask:0xf
	v_fmac_f32_dpp v131, -v141, v95 row_newbcast:9 row_mask:0xf bank_mask:0xf
	v_fmac_f32_dpp v132, -v141, v96 row_newbcast:10 row_mask:0xf bank_mask:0xf
	v_fmac_f32_dpp v133, -v141, v93 row_newbcast:7 row_mask:0xf bank_mask:0xf
	s_nop 1
	v_fmac_f32_dpp v133, -v141, v97 row_newbcast:11 row_mask:0xf bank_mask:0xf
	v_add_f32_e32 v20, v4, v131
	v_add_f32_e32 v21, v132, v133
	v_add_f32_e32 v72, v20, v21
	ds_read_b32 v140, v138 offset:768
	ds_read_b32 v141, v138 offset:832
	s_waitcnt lgkmcnt(4)
	v_mul_f32_dpp v137, -v148, v73 row_newbcast:3 row_mask:0xf bank_mask:0xf
	v_fmac_f32_dpp v3, -v148, v74 row_newbcast:4 row_mask:0xf bank_mask:0xf
	v_mul_f32_dpp v135, -v148, v75 row_newbcast:5 row_mask:0xf bank_mask:0xf
	v_mul_f32_dpp v136, -v148, v72 row_newbcast:2 row_mask:0xf bank_mask:0xf
	v_fmac_f32_dpp v137, -v148, v77 row_newbcast:7 row_mask:0xf bank_mask:0xf
	v_fmac_f32_dpp v3, -v148, v78 row_newbcast:8 row_mask:0xf bank_mask:0xf
	v_fmac_f32_dpp v135, -v148, v79 row_newbcast:9 row_mask:0xf bank_mask:0xf
	v_fmac_f32_dpp v136, -v148, v76 row_newbcast:6 row_mask:0xf bank_mask:0xf
	v_fmac_f32_dpp v137, -v148, v81 row_newbcast:11 row_mask:0xf bank_mask:0xf
	v_fmac_f32_dpp v3, -v148, v82 row_newbcast:12 row_mask:0xf bank_mask:0xf
	v_fmac_f32_dpp v135, -v148, v83 row_newbcast:13 row_mask:0xf bank_mask:0xf
	v_fmac_f32_dpp v136, -v148, v80 row_newbcast:10 row_mask:0xf bank_mask:0xf
	v_fmac_f32_dpp v137, -v148, v85 row_newbcast:15 row_mask:0xf bank_mask:0xf
	v_fmac_f32_dpp v3, -v149, v86 row_newbcast:0 row_mask:0xf bank_mask:0xf
	v_fmac_f32_dpp v135, -v149, v87 row_newbcast:1 row_mask:0xf bank_mask:0xf
	v_fmac_f32_dpp v136, -v148, v84 row_newbcast:14 row_mask:0xf bank_mask:0xf
	v_fmac_f32_dpp v137, -v149, v89 row_newbcast:3 row_mask:0xf bank_mask:0xf
	v_fmac_f32_dpp v3, -v149, v90 row_newbcast:4 row_mask:0xf bank_mask:0xf
	v_fmac_f32_dpp v135, -v149, v91 row_newbcast:5 row_mask:0xf bank_mask:0xf
	v_fmac_f32_dpp v136, -v149, v88 row_newbcast:2 row_mask:0xf bank_mask:0xf
	v_fmac_f32_dpp v137, -v149, v93 row_newbcast:7 row_mask:0xf bank_mask:0xf
	v_fmac_f32_dpp v3, -v149, v94 row_newbcast:8 row_mask:0xf bank_mask:0xf
	v_fmac_f32_dpp v135, -v149, v95 row_newbcast:9 row_mask:0xf bank_mask:0xf
	v_fmac_f32_dpp v136, -v149, v92 row_newbcast:6 row_mask:0xf bank_mask:0xf
	v_fmac_f32_dpp v137, -v149, v97 row_newbcast:11 row_mask:0xf bank_mask:0xf
	s_nop 0
	v_fmac_f32_dpp v136, -v149, v96 row_newbcast:10 row_mask:0xf bank_mask:0xf
	v_add_f32_e32 v20, v3, v135
	v_add_f32_e32 v21, v136, v137
	v_add_f32_e32 v71, v20, v21
	ds_read_b32 v148, v138 offset:512
	ds_read_b32 v149, v138 offset:576
	s_waitcnt lgkmcnt(4)
	v_mul_f32_dpp v132, -v144, v72 row_newbcast:2 row_mask:0xf bank_mask:0xf
	v_mul_f32_dpp v133, -v144, v73 row_newbcast:3 row_mask:0xf bank_mask:0xf
	v_fmac_f32_dpp v2, -v144, v74 row_newbcast:4 row_mask:0xf bank_mask:0xf
	v_mul_f32_dpp v131, -v144, v71 row_newbcast:1 row_mask:0xf bank_mask:0xf
	v_fmac_f32_dpp v132, -v144, v76 row_newbcast:6 row_mask:0xf bank_mask:0xf
	v_fmac_f32_dpp v133, -v144, v77 row_newbcast:7 row_mask:0xf bank_mask:0xf
	v_fmac_f32_dpp v2, -v144, v78 row_newbcast:8 row_mask:0xf bank_mask:0xf
	v_fmac_f32_dpp v131, -v144, v75 row_newbcast:5 row_mask:0xf bank_mask:0xf
	v_fmac_f32_dpp v132, -v144, v80 row_newbcast:10 row_mask:0xf bank_mask:0xf
	v_fmac_f32_dpp v133, -v144, v81 row_newbcast:11 row_mask:0xf bank_mask:0xf
	v_fmac_f32_dpp v2, -v144, v82 row_newbcast:12 row_mask:0xf bank_mask:0xf
	v_fmac_f32_dpp v131, -v144, v79 row_newbcast:9 row_mask:0xf bank_mask:0xf
	v_fmac_f32_dpp v132, -v144, v84 row_newbcast:14 row_mask:0xf bank_mask:0xf
	v_fmac_f32_dpp v133, -v144, v85 row_newbcast:15 row_mask:0xf bank_mask:0xf
	v_fmac_f32_dpp v2, -v145, v86 row_newbcast:0 row_mask:0xf bank_mask:0xf
	v_fmac_f32_dpp v131, -v144, v83 row_newbcast:13 row_mask:0xf bank_mask:0xf
	v_fmac_f32_dpp v132, -v145, v88 row_newbcast:2 row_mask:0xf bank_mask:0xf
	v_fmac_f32_dpp v133, -v145, v89 row_newbcast:3 row_mask:0xf bank_mask:0xf
	v_fmac_f32_dpp v2, -v145, v90 row_newbcast:4 row_mask:0xf bank_mask:0xf
	v_fmac_f32_dpp v131, -v145, v87 row_newbcast:1 row_mask:0xf bank_mask:0xf
	v_fmac_f32_dpp v132, -v145, v92 row_newbcast:6 row_mask:0xf bank_mask:0xf
	v_fmac_f32_dpp v133, -v145, v93 row_newbcast:7 row_mask:0xf bank_mask:0xf
	v_fmac_f32_dpp v2, -v145, v94 row_newbcast:8 row_mask:0xf bank_mask:0xf
	v_fmac_f32_dpp v131, -v145, v91 row_newbcast:5 row_mask:0xf bank_mask:0xf
	v_fmac_f32_dpp v132, -v145, v96 row_newbcast:10 row_mask:0xf bank_mask:0xf
	v_fmac_f32_dpp v133, -v145, v97 row_newbcast:11 row_mask:0xf bank_mask:0xf
	v_fmac_f32_dpp v131, -v145, v95 row_newbcast:9 row_mask:0xf bank_mask:0xf
	v_add_f32_e32 v20, v2, v131
	v_add_f32_e32 v21, v132, v133
	v_add_f32_e32 v70, v20, v21
	ds_read_b32 v144, v138 offset:256
	ds_read_b32 v145, v138 offset:320
	s_waitcnt lgkmcnt(4)
	v_mul_f32_dpp v135, -v140, v71 row_newbcast:1 row_mask:0xf bank_mask:0xf
	v_mul_f32_dpp v136, -v140, v72 row_newbcast:2 row_mask:0xf bank_mask:0xf
	v_mul_f32_dpp v137, -v140, v73 row_newbcast:3 row_mask:0xf bank_mask:0xf
	v_fmac_f32_dpp v163, -v140, v70 row_newbcast:0 row_mask:0xf bank_mask:0xf
	v_fmac_f32_dpp v135, -v140, v75 row_newbcast:5 row_mask:0xf bank_mask:0xf
	v_fmac_f32_dpp v136, -v140, v76 row_newbcast:6 row_mask:0xf bank_mask:0xf
	v_fmac_f32_dpp v137, -v140, v77 row_newbcast:7 row_mask:0xf bank_mask:0xf
	v_fmac_f32_dpp v163, -v140, v74 row_newbcast:4 row_mask:0xf bank_mask:0xf
	v_fmac_f32_dpp v135, -v140, v79 row_newbcast:9 row_mask:0xf bank_mask:0xf
	v_fmac_f32_dpp v136, -v140, v80 row_newbcast:10 row_mask:0xf bank_mask:0xf
	v_fmac_f32_dpp v137, -v140, v81 row_newbcast:11 row_mask:0xf bank_mask:0xf
	v_fmac_f32_dpp v163, -v140, v78 row_newbcast:8 row_mask:0xf bank_mask:0xf
	v_fmac_f32_dpp v135, -v140, v83 row_newbcast:13 row_mask:0xf bank_mask:0xf
	v_fmac_f32_dpp v136, -v140, v84 row_newbcast:14 row_mask:0xf bank_mask:0xf
	v_fmac_f32_dpp v137, -v140, v85 row_newbcast:15 row_mask:0xf bank_mask:0xf
	v_fmac_f32_dpp v163, -v140, v82 row_newbcast:12 row_mask:0xf bank_mask:0xf
	v_fmac_f32_dpp v135, -v141, v87 row_newbcast:1 row_mask:0xf bank_mask:0xf
	v_fmac_f32_dpp v136, -v141, v88 row_newbcast:2 row_mask:0xf bank_mask:0xf
	v_fmac_f32_dpp v137, -v141, v89 row_newbcast:3 row_mask:0xf bank_mask:0xf
	v_fmac_f32_dpp v163, -v141, v86 row_newbcast:0 row_mask:0xf bank_mask:0xf
	v_fmac_f32_dpp v135, -v141, v91 row_newbcast:5 row_mask:0xf bank_mask:0xf
	v_fmac_f32_dpp v136, -v141, v92 row_newbcast:6 row_mask:0xf bank_mask:0xf
	v_fmac_f32_dpp v137, -v141, v93 row_newbcast:7 row_mask:0xf bank_mask:0xf
	v_fmac_f32_dpp v163, -v141, v90 row_newbcast:4 row_mask:0xf bank_mask:0xf
	v_fmac_f32_dpp v135, -v141, v95 row_newbcast:9 row_mask:0xf bank_mask:0xf
	v_fmac_f32_dpp v136, -v141, v96 row_newbcast:10 row_mask:0xf bank_mask:0xf
	v_fmac_f32_dpp v137, -v141, v97 row_newbcast:11 row_mask:0xf bank_mask:0xf
	v_fmac_f32_dpp v163, -v141, v94 row_newbcast:8 row_mask:0xf bank_mask:0xf
	v_add_f32_e32 v20, v163, v135
	v_add_f32_e32 v21, v136, v137
	v_add_f32_e32 v69, v20, v21
	ds_read_b32 v140, v138 offset:0
	ds_read_b32 v141, v138 offset:64
	s_waitcnt lgkmcnt(4)
	v_fmac_f32_dpp v162, -v148, v70 row_newbcast:4 row_mask:0xf bank_mask:0xf
	v_mul_f32_dpp v131, -v148, v71 row_newbcast:5 row_mask:0xf bank_mask:0xf
	v_mul_f32_dpp v132, -v148, v72 row_newbcast:6 row_mask:0xf bank_mask:0xf
	v_mul_f32_dpp v133, -v148, v69 row_newbcast:3 row_mask:0xf bank_mask:0xf
	v_fmac_f32_dpp v162, -v148, v74 row_newbcast:8 row_mask:0xf bank_mask:0xf
	v_fmac_f32_dpp v131, -v148, v75 row_newbcast:9 row_mask:0xf bank_mask:0xf
	v_fmac_f32_dpp v132, -v148, v76 row_newbcast:10 row_mask:0xf bank_mask:0xf
	v_fmac_f32_dpp v133, -v148, v73 row_newbcast:7 row_mask:0xf bank_mask:0xf
	v_fmac_f32_dpp v162, -v148, v78 row_newbcast:12 row_mask:0xf bank_mask:0xf
	v_fmac_f32_dpp v131, -v148, v79 row_newbcast:13 row_mask:0xf bank_mask:0xf
	v_fmac_f32_dpp v132, -v148, v80 row_newbcast:14 row_mask:0xf bank_mask:0xf
	v_fmac_f32_dpp v133, -v148, v77 row_newbcast:11 row_mask:0xf bank_mask:0xf
	v_fmac_f32_dpp v162, -v149, v82 row_newbcast:0 row_mask:0xf bank_mask:0xf
	v_fmac_f32_dpp v131, -v149, v83 row_newbcast:1 row_mask:0xf bank_mask:0xf
	v_fmac_f32_dpp v132, -v149, v84 row_newbcast:2 row_mask:0xf bank_mask:0xf
	v_fmac_f32_dpp v133, -v148, v81 row_newbcast:15 row_mask:0xf bank_mask:0xf
	v_fmac_f32_dpp v162, -v149, v86 row_newbcast:4 row_mask:0xf bank_mask:0xf
	v_fmac_f32_dpp v131, -v149, v87 row_newbcast:5 row_mask:0xf bank_mask:0xf
	v_fmac_f32_dpp v132, -v149, v88 row_newbcast:6 row_mask:0xf bank_mask:0xf
	v_fmac_f32_dpp v133, -v149, v85 row_newbcast:3 row_mask:0xf bank_mask:0xf
	v_fmac_f32_dpp v162, -v149, v90 row_newbcast:8 row_mask:0xf bank_mask:0xf
	v_fmac_f32_dpp v131, -v149, v91 row_newbcast:9 row_mask:0xf bank_mask:0xf
	v_fmac_f32_dpp v132, -v149, v92 row_newbcast:10 row_mask:0xf bank_mask:0xf
	v_fmac_f32_dpp v133, -v149, v89 row_newbcast:7 row_mask:0xf bank_mask:0xf
	v_fmac_f32_dpp v162, -v149, v94 row_newbcast:12 row_mask:0xf bank_mask:0xf
	v_fmac_f32_dpp v131, -v149, v95 row_newbcast:13 row_mask:0xf bank_mask:0xf
	v_fmac_f32_dpp v132, -v149, v96 row_newbcast:14 row_mask:0xf bank_mask:0xf
	v_fmac_f32_dpp v133, -v149, v93 row_newbcast:11 row_mask:0xf bank_mask:0xf
	s_nop 1
	v_fmac_f32_dpp v133, -v149, v97 row_newbcast:15 row_mask:0xf bank_mask:0xf
	v_add_f32_e32 v20, v162, v131
	v_add_f32_e32 v21, v132, v133
	v_add_f32_e32 v68, v20, v21
	s_waitcnt lgkmcnt(2)
	v_mul_f32_dpp v137, -v144, v69 row_newbcast:3 row_mask:0xf bank_mask:0xf
	v_fmac_f32_dpp v161, -v144, v70 row_newbcast:4 row_mask:0xf bank_mask:0xf
	v_mul_f32_dpp v135, -v144, v71 row_newbcast:5 row_mask:0xf bank_mask:0xf
	v_mul_f32_dpp v136, -v144, v68 row_newbcast:2 row_mask:0xf bank_mask:0xf
	v_fmac_f32_dpp v137, -v144, v73 row_newbcast:7 row_mask:0xf bank_mask:0xf
	v_fmac_f32_dpp v161, -v144, v74 row_newbcast:8 row_mask:0xf bank_mask:0xf
	v_fmac_f32_dpp v135, -v144, v75 row_newbcast:9 row_mask:0xf bank_mask:0xf
	v_fmac_f32_dpp v136, -v144, v72 row_newbcast:6 row_mask:0xf bank_mask:0xf
	v_fmac_f32_dpp v137, -v144, v77 row_newbcast:11 row_mask:0xf bank_mask:0xf
	v_fmac_f32_dpp v161, -v144, v78 row_newbcast:12 row_mask:0xf bank_mask:0xf
	v_fmac_f32_dpp v135, -v144, v79 row_newbcast:13 row_mask:0xf bank_mask:0xf
	v_fmac_f32_dpp v136, -v144, v76 row_newbcast:10 row_mask:0xf bank_mask:0xf
	v_fmac_f32_dpp v137, -v144, v81 row_newbcast:15 row_mask:0xf bank_mask:0xf
	v_fmac_f32_dpp v161, -v145, v82 row_newbcast:0 row_mask:0xf bank_mask:0xf
	v_fmac_f32_dpp v135, -v145, v83 row_newbcast:1 row_mask:0xf bank_mask:0xf
	v_fmac_f32_dpp v136, -v144, v80 row_newbcast:14 row_mask:0xf bank_mask:0xf
	v_fmac_f32_dpp v137, -v145, v85 row_newbcast:3 row_mask:0xf bank_mask:0xf
	v_fmac_f32_dpp v161, -v145, v86 row_newbcast:4 row_mask:0xf bank_mask:0xf
	v_fmac_f32_dpp v135, -v145, v87 row_newbcast:5 row_mask:0xf bank_mask:0xf
	v_fmac_f32_dpp v136, -v145, v84 row_newbcast:2 row_mask:0xf bank_mask:0xf
	v_fmac_f32_dpp v137, -v145, v89 row_newbcast:7 row_mask:0xf bank_mask:0xf
	v_fmac_f32_dpp v161, -v145, v90 row_newbcast:8 row_mask:0xf bank_mask:0xf
	v_fmac_f32_dpp v135, -v145, v91 row_newbcast:9 row_mask:0xf bank_mask:0xf
	v_fmac_f32_dpp v136, -v145, v88 row_newbcast:6 row_mask:0xf bank_mask:0xf
	v_fmac_f32_dpp v137, -v145, v93 row_newbcast:11 row_mask:0xf bank_mask:0xf
	v_fmac_f32_dpp v161, -v145, v94 row_newbcast:12 row_mask:0xf bank_mask:0xf
	v_fmac_f32_dpp v135, -v145, v95 row_newbcast:13 row_mask:0xf bank_mask:0xf
	v_fmac_f32_dpp v136, -v145, v92 row_newbcast:10 row_mask:0xf bank_mask:0xf
	v_fmac_f32_dpp v137, -v145, v97 row_newbcast:15 row_mask:0xf bank_mask:0xf
	s_nop 0
	v_fmac_f32_dpp v136, -v145, v96 row_newbcast:14 row_mask:0xf bank_mask:0xf
	v_add_f32_e32 v20, v161, v135
	v_add_f32_e32 v21, v136, v137
	v_add_f32_e32 v67, v20, v21
	s_waitcnt lgkmcnt(0)
	v_mul_f32_dpp v132, -v140, v68 row_newbcast:2 row_mask:0xf bank_mask:0xf
	v_mul_f32_dpp v133, -v140, v69 row_newbcast:3 row_mask:0xf bank_mask:0xf
	v_fmac_f32_dpp v160, -v140, v70 row_newbcast:4 row_mask:0xf bank_mask:0xf
	v_mul_f32_dpp v131, -v140, v67 row_newbcast:1 row_mask:0xf bank_mask:0xf
	v_fmac_f32_dpp v132, -v140, v72 row_newbcast:6 row_mask:0xf bank_mask:0xf
	v_fmac_f32_dpp v133, -v140, v73 row_newbcast:7 row_mask:0xf bank_mask:0xf
	v_fmac_f32_dpp v160, -v140, v74 row_newbcast:8 row_mask:0xf bank_mask:0xf
	v_fmac_f32_dpp v131, -v140, v71 row_newbcast:5 row_mask:0xf bank_mask:0xf
	v_fmac_f32_dpp v132, -v140, v76 row_newbcast:10 row_mask:0xf bank_mask:0xf
	v_fmac_f32_dpp v133, -v140, v77 row_newbcast:11 row_mask:0xf bank_mask:0xf
	v_fmac_f32_dpp v160, -v140, v78 row_newbcast:12 row_mask:0xf bank_mask:0xf
	v_fmac_f32_dpp v131, -v140, v75 row_newbcast:9 row_mask:0xf bank_mask:0xf
	v_fmac_f32_dpp v132, -v140, v80 row_newbcast:14 row_mask:0xf bank_mask:0xf
	v_fmac_f32_dpp v133, -v140, v81 row_newbcast:15 row_mask:0xf bank_mask:0xf
	v_fmac_f32_dpp v160, -v141, v82 row_newbcast:0 row_mask:0xf bank_mask:0xf
	v_fmac_f32_dpp v131, -v140, v79 row_newbcast:13 row_mask:0xf bank_mask:0xf
	v_fmac_f32_dpp v132, -v141, v84 row_newbcast:2 row_mask:0xf bank_mask:0xf
	v_fmac_f32_dpp v133, -v141, v85 row_newbcast:3 row_mask:0xf bank_mask:0xf
	v_fmac_f32_dpp v160, -v141, v86 row_newbcast:4 row_mask:0xf bank_mask:0xf
	v_fmac_f32_dpp v131, -v141, v83 row_newbcast:1 row_mask:0xf bank_mask:0xf
	v_fmac_f32_dpp v132, -v141, v88 row_newbcast:6 row_mask:0xf bank_mask:0xf
	v_fmac_f32_dpp v133, -v141, v89 row_newbcast:7 row_mask:0xf bank_mask:0xf
	v_fmac_f32_dpp v160, -v141, v90 row_newbcast:8 row_mask:0xf bank_mask:0xf
	v_fmac_f32_dpp v131, -v141, v87 row_newbcast:5 row_mask:0xf bank_mask:0xf
	v_fmac_f32_dpp v132, -v141, v92 row_newbcast:10 row_mask:0xf bank_mask:0xf
	v_fmac_f32_dpp v133, -v141, v93 row_newbcast:11 row_mask:0xf bank_mask:0xf
	v_fmac_f32_dpp v160, -v141, v94 row_newbcast:12 row_mask:0xf bank_mask:0xf
	v_fmac_f32_dpp v131, -v141, v91 row_newbcast:9 row_mask:0xf bank_mask:0xf
	v_fmac_f32_dpp v132, -v141, v96 row_newbcast:14 row_mask:0xf bank_mask:0xf
	v_fmac_f32_dpp v133, -v141, v97 row_newbcast:15 row_mask:0xf bank_mask:0xf
	v_fmac_f32_dpp v131, -v141, v95 row_newbcast:13 row_mask:0xf bank_mask:0xf
	v_add_f32_e32 v20, v160, v131
	v_add_f32_e32 v21, v132, v133
	v_add_f32_e32 v66, v20, v21
	v_mov_b32_e32 v19, s5
	v_and_b32_e32 v20, 31, v1
	v_lshlrev_b32_e32 v20, 4, v20
	v_cmp_lt_u32_e32 vcc, 31, v1
	s_nop 1
	v_cndmask_b32_e32 v21, 0, v193, vcc
	v_or_b32_e32 v21, v21, v20
	v_add_u32_e32 v20, 0x1000, v20
	ds_read_b128 v[194:197], v19 offset:0
	ds_read_b128 v[198:201], v19 offset:32
	ds_read_b128 v[202:205], v19 offset:16
	ds_read_b128 v[206:209], v19 offset:48
	ds_read_b128 v[210:213], v19 offset:64
	ds_read_b128 v[214:217], v19 offset:96
	ds_read_b128 v[218:221], v19 offset:80
	ds_read_b128 v[222:225], v19 offset:112
	s_waitcnt lgkmcnt(6)
	v_pk_mul_f32 v[2:3], v[66:67], v[194:195]
	v_pk_mul_f32 v[4:5], v[68:69], v[196:197]
	v_pk_mul_f32 v[6:7], v[74:75], v[198:199]
	v_pk_mul_f32 v[8:9], v[76:77], v[200:201]
	v_cvt_pk_bf16_f32 v10, v2, v3
	v_cvt_pk_bf16_f32 v11, v4, v5
	v_cvt_pk_bf16_f32 v12, v6, v7
	v_cvt_pk_bf16_f32 v13, v8, v9
	global_store_dwordx4 v21, v[10:13], s[6:7] sc0 sc1
	s_waitcnt lgkmcnt(4)
	v_pk_mul_f32 v[2:3], v[70:71], v[202:203]
	v_pk_mul_f32 v[4:5], v[72:73], v[204:205]
	v_pk_mul_f32 v[6:7], v[78:79], v[206:207]
	v_pk_mul_f32 v[8:9], v[80:81], v[208:209]
	v_cvt_pk_bf16_f32 v14, v2, v3
	v_cvt_pk_bf16_f32 v15, v4, v5
	v_cvt_pk_bf16_f32 v16, v6, v7
	v_cvt_pk_bf16_f32 v17, v8, v9
	global_store_dwordx4 v21, v[14:17], s[6:7] offset:512 sc0 sc1
	s_waitcnt lgkmcnt(2)
	v_pk_mul_f32 v[2:3], v[82:83], v[210:211]
	v_pk_mul_f32 v[4:5], v[84:85], v[212:213]
	v_pk_mul_f32 v[6:7], v[90:91], v[214:215]
	v_pk_mul_f32 v[8:9], v[92:93], v[216:217]
	v_cvt_pk_bf16_f32 v10, v2, v3
	v_cvt_pk_bf16_f32 v11, v4, v5
	v_cvt_pk_bf16_f32 v12, v6, v7
	v_cvt_pk_bf16_f32 v13, v8, v9
	global_store_dwordx4 v21, v[10:13], s[6:7] offset:1024 sc0 sc1
	s_waitcnt lgkmcnt(0)
	v_pk_mul_f32 v[2:3], v[86:87], v[218:219]
	v_pk_mul_f32 v[4:5], v[88:89], v[220:221]
	v_pk_mul_f32 v[6:7], v[94:95], v[222:223]
	v_pk_mul_f32 v[8:9], v[96:97], v[224:225]
	v_cvt_pk_bf16_f32 v14, v2, v3
	v_cvt_pk_bf16_f32 v15, v4, v5
	v_cvt_pk_bf16_f32 v16, v6, v7
	v_cvt_pk_bf16_f32 v17, v8, v9
	global_store_dwordx4 v21, v[14:17], s[6:7] offset:1536 sc0 sc1
	s_and_saveexec_b64 s[0:1], vcc
	s_cbranch_execz .LBB0_655
	ds_read_b128 v[194:197], v19 offset:128
	ds_read_b128 v[198:201], v19 offset:160
	ds_read_b128 v[202:205], v19 offset:144
	ds_read_b128 v[206:209], v19 offset:176
	ds_read_b128 v[210:213], v19 offset:192
	ds_read_b128 v[214:217], v19 offset:224
	ds_read_b128 v[218:221], v19 offset:208
	ds_read_b128 v[222:225], v19 offset:240
	s_waitcnt lgkmcnt(6)
	v_pk_mul_f32 v[2:3], v[98:99], v[194:195]
	v_pk_mul_f32 v[4:5], v[100:101], v[196:197]
	v_pk_mul_f32 v[6:7], v[106:107], v[198:199]
	v_pk_mul_f32 v[8:9], v[108:109], v[200:201]
	v_cvt_pk_bf16_f32 v10, v2, v3
	v_cvt_pk_bf16_f32 v11, v4, v5
	v_cvt_pk_bf16_f32 v12, v6, v7
	v_cvt_pk_bf16_f32 v13, v8, v9
	global_store_dwordx4 v20, v[10:13], s[6:7] sc0 sc1
	s_waitcnt lgkmcnt(4)
	v_pk_mul_f32 v[2:3], v[102:103], v[202:203]
	v_pk_mul_f32 v[4:5], v[104:105], v[204:205]
	v_pk_mul_f32 v[6:7], v[110:111], v[206:207]
	v_pk_mul_f32 v[8:9], v[112:113], v[208:209]
	v_cvt_pk_bf16_f32 v14, v2, v3
	v_cvt_pk_bf16_f32 v15, v4, v5
	v_cvt_pk_bf16_f32 v16, v6, v7
	v_cvt_pk_bf16_f32 v17, v8, v9
	global_store_dwordx4 v20, v[14:17], s[6:7] offset:512 sc0 sc1
	s_waitcnt lgkmcnt(2)
	v_pk_mul_f32 v[2:3], v[114:115], v[210:211]
	v_pk_mul_f32 v[4:5], v[116:117], v[212:213]
	v_pk_mul_f32 v[6:7], v[122:123], v[214:215]
	v_pk_mul_f32 v[8:9], v[124:125], v[216:217]
	v_cvt_pk_bf16_f32 v10, v2, v3
	v_cvt_pk_bf16_f32 v11, v4, v5
	v_cvt_pk_bf16_f32 v12, v6, v7
	v_cvt_pk_bf16_f32 v13, v8, v9
	global_store_dwordx4 v20, v[10:13], s[6:7] offset:1024 sc0 sc1
	s_waitcnt lgkmcnt(0)
	v_pk_mul_f32 v[2:3], v[118:119], v[218:219]
	v_pk_mul_f32 v[4:5], v[120:121], v[220:221]
	v_pk_mul_f32 v[6:7], v[126:127], v[222:223]
	v_pk_mul_f32 v[8:9], v[128:129], v[224:225]
	v_cvt_pk_bf16_f32 v14, v2, v3
	v_cvt_pk_bf16_f32 v15, v4, v5
	v_cvt_pk_bf16_f32 v16, v6, v7
	v_cvt_pk_bf16_f32 v17, v8, v9
	global_store_dwordx4 v20, v[14:17], s[6:7] offset:1536 sc0 sc1
	s_nop 1
